# H epilogue: bf16 hn row pieces exchanged with v_permlane16_swap and stored as dwordx4 (was 4x dwordx2 per row); phase C: next unit's q/k/v rows touched during S2-S4 (L2 prefetch), S1 16-lane l2-norm s
# speedup vs baseline: 1.0072x; 1.0072x over previous
; __device__ __forceinline__ float bflo(unsigned w) { return __uint_as_float(w << 16); }
; __device__ __forceinline__ float bfhi(unsigned w) { return __uint_as_float(w & 0xffff0000u); }
; __device__ __forceinline__ float bflo(unsigned w) { return __uint_as_float(w << 16); }
; __device__ __forceinline__ float bfhi(unsigned w) { return __uint_as_float(w & 0xffff0000u); }
; #define conv_w INP(4)
; __device__ __forceinline__ void gdn_prep_unit(LAS unsigned char* lds, unsigned char* ws, const float* conv_w, const float* a_log, const float* dt_bias,
;                                               int l, int Tp, int ci, int h, int nci, int nh, unsigned& pre_ba, int tid, int wave, int lane) {
;     ...
;             const float* cw = conv_w + (size_t)l * 3 * 3072 + chan;
;             const f32x4 w0a = *(const f32x4*)cw, w0b = *(const f32x4*)(cw + 4), w1a = *(const f32x4*)(cw + 3072), w1b = *(const f32x4*)(cw + 3072 + 4), w2a = *(const f32x4*)(cw + 6144), w2b = *(const f32x4*)(cw + 6144 + 4);
;             const float w0[8] = {w0a.x, w0a.y, w0a.z, w0a.w, w0b.x, w0b.y, w0b.z, w0b.w}, w1[8] = {w1a.x, w1a.y, w1a.z, w1a.w, w1b.x, w1b.y, w1b.z, w1b.w}, w2[8] = {w2a.x, w2a.y, w2a.z, w2a.w, w2b.x, w2b.y, w2b.z, w2b.w};
;             const float a0[8] = {bflo(x0.x), bfhi(x0.x), bflo(x0.y), bfhi(x0.y), bflo(x0.z), bfhi(x0.z), bflo(x0.w), bfhi(x0.w)};
;             const float a1[8] = {bflo(x1.x), bfhi(x1.x), bflo(x1.y), bfhi(x1.y), bflo(x1.z), bfhi(x1.z), bflo(x1.w), bfhi(x1.w)};
;             const float a2[8] = {bflo(x2.x), bfhi(x2.x), bflo(x2.y), bfhi(x2.y), bflo(x2.z), bfhi(x2.z), bflo(x2.w), bfhi(x2.w)};
;             float y[8]; float ss = 0.f;
; #pragma unroll
;             for (int e = 0; e < 8; ++e) { const float a = a0[e] * w0[e] + a1[e] * w1[e] + a2[e] * w2[e]; y[e] = a * __builtin_amdgcn_rcpf(1.0f + __expf(-a)); ss += y[e] * y[e]; }
;             if (mat < 2) {
;                 ss += xshfl<1>(ss); ss += xshfl<2>(ss); ss += xshfl<4>(ss); ss += xshfl<8>(ss);
;                 float rs = __builtin_amdgcn_rsqf(ss + NORM_EPS); if (mat == 0) rs *= 0.08838834764831845f;
; #pragma unroll
;                 for (int e = 0; e < 8; ++e) y[e] *= rs;
;             }
.LBB0_330:
	s_or_b64 exec, exec, s[90:91]
	v_lshl_add_u64 v[26:27], v[10:11], 2, s[44:45]
	s_mov_b64 s[4:5], 0x3000
	v_add_co_u32_e32 v12, vcc, 0x3000, v26
	v_lshl_add_u64 v[10:11], v[26:27], 0, s[4:5]
	s_nop 0
	v_addc_co_u32_e32 v13, vcc, 0, v27, vcc
	s_mov_b64 s[4:5], 0x6000
	s_movk_i32 s3, 0x6000
	global_load_dwordx4 v[22:25], v[26:27], off offset:16
	global_load_dwordx4 v[32:35], v[26:27], off
	global_load_dwordx4 v[212:215], v[12:13], off
	s_nop 0
	global_load_dwordx4 v[10:13], v[10:11], off offset:16
	v_lshl_add_u64 v[28:29], v[26:27], 0, s[4:5]
	v_add_co_u32_e32 v26, vcc, s3, v26
	s_waitcnt vmcnt(4)
	v_lshlrev_b32_e32 v196, 16, v6
	v_addc_co_u32_e32 v27, vcc, 0, v27, vcc
	global_load_dwordx4 v[216:219], v[26:27], off
	s_nop 0
	global_load_dwordx4 v[26:29], v[28:29], off offset:16
	v_and_b32_e32 v197, 0xffff0000, v6
	v_lshlrev_b32_e32 v36, 16, v14
	v_and_b32_e32 v37, 0xffff0000, v14
	v_lshlrev_b32_e32 v228, 16, v18
	v_and_b32_e32 v229, 0xffff0000, v18
	v_lshlrev_b32_e32 v14, 16, v15
	v_and_b32_e32 v15, 0xffff0000, v15
	v_lshlrev_b32_e32 v18, 16, v19
	v_and_b32_e32 v19, 0xffff0000, v19
	v_lshlrev_b32_e32 v230, 16, v21
	v_lshlrev_b32_e32 v211, 16, v17
	v_readlane_b32 s4, v254, 34
	v_readlane_b32 s5, v254, 35
	s_waitcnt vmcnt(3)
	v_pk_mul_f32 v[196:197], v[212:213], v[196:197]
	s_nop 0
	v_pk_fma_f32 v[32:33], v[32:33], v[36:37], v[196:197]
	s_waitcnt vmcnt(1)
	v_pk_fma_f32 v[32:33], v[216:217], v[228:229], v[32:33]
	s_nop 0
	v_mul_f32_e32 v6, 0xbfb8aa3b, v32
	v_exp_f32_e32 v6, v6
	s_nop 0
	v_add_f32_e32 v6, 1.0, v6
	v_rcp_f32_e32 v36, v6
	v_mul_f32_e32 v6, 0xbfb8aa3b, v33
	v_exp_f32_e32 v6, v6
	s_nop 0
	v_add_f32_e32 v6, 1.0, v6
	v_rcp_f32_e32 v37, v6
	v_lshlrev_b32_e32 v6, 16, v7
	v_and_b32_e32 v7, 0xffff0000, v7
	v_pk_mul_f32 v[6:7], v[214:215], v[6:7]
	v_pk_mul_f32 v[32:33], v[32:33], v[36:37]
	v_pk_fma_f32 v[6:7], v[34:35], v[14:15], v[6:7]
	v_and_b32_e32 v35, 0xffff0000, v20
	v_pk_fma_f32 v[6:7], v[218:219], v[18:19], v[6:7]
	v_and_b32_e32 v19, 0xffff0000, v8
	v_mul_f32_e32 v14, 0xbfb8aa3b, v6
	v_mul_f32_e32 v15, 0xbfb8aa3b, v7
	v_exp_f32_e32 v14, v14
	v_exp_f32_e32 v15, v15
	v_lshlrev_b32_e32 v18, 16, v8
	v_pk_mul_f32 v[10:11], v[10:11], v[18:19]
	v_add_f32_e32 v14, 1.0, v14
	v_add_f32_e32 v15, 1.0, v15
	v_rcp_f32_e32 v14, v14
	v_rcp_f32_e32 v15, v15
	v_lshlrev_b32_e32 v34, 16, v20
	v_and_b32_e32 v19, 0xffff0000, v21
	v_and_b32_e32 v18, 0xffff0000, v17
	v_pk_mul_f32 v[6:7], v[6:7], v[14:15]
	v_and_b32_e32 v15, 0xffff0000, v16
	v_lshlrev_b32_e32 v14, 16, v16
	v_pk_fma_f32 v[10:11], v[22:23], v[14:15], v[10:11]
	s_waitcnt vmcnt(0)
	v_pk_fma_f32 v[10:11], v[26:27], v[34:35], v[10:11]
	s_nop 0
	v_mul_f32_e32 v8, 0xbfb8aa3b, v10
	v_exp_f32_e32 v8, v8
	s_nop 0
	v_add_f32_e32 v8, 1.0, v8
	v_rcp_f32_e32 v14, v8
	v_mul_f32_e32 v8, 0xbfb8aa3b, v11
	v_exp_f32_e32 v8, v8
	s_nop 0
	v_add_f32_e32 v8, 1.0, v8
	v_rcp_f32_e32 v15, v8
	v_mul_f32_e32 v8, v24, v211
	v_pk_mul_f32 v[10:11], v[10:11], v[14:15]
	v_mul_f32_e32 v14, v28, v230
	v_mov_b32_e32 v28, v25
	v_pk_mul_f32 v[16:17], v[28:29], v[18:19]
	v_and_b32_e32 v19, 0xffff0000, v9
	v_lshlrev_b32_e32 v18, 16, v9
	v_mov_b32_e32 v9, v16
	v_pk_fma_f32 v[8:9], v[12:13], v[18:19], v[8:9]
	v_mov_b32_e32 v15, v17
	v_pk_add_f32 v[8:9], v[8:9], v[14:15]
	s_nop 0
	v_mul_f32_e32 v12, 0xbfb8aa3b, v8
	v_mul_f32_e32 v13, 0xbfb8aa3b, v9
	v_exp_f32_e32 v12, v12
	v_exp_f32_e32 v13, v13
	v_add_f32_e32 v12, 1.0, v12
	v_add_f32_e32 v13, 1.0, v13
	v_rcp_f32_e32 v12, v12
	v_rcp_f32_e32 v13, v13
	s_nop 0
	v_pk_mul_f32 v[8:9], v[8:9], v[12:13]
	s_and_saveexec_b64 s[90:91], s[4:5]
	s_cbranch_execz .LBB0_332
	v_pk_mul_f32 v[12:13], v[32:33], v[32:33]
	v_pk_mul_f32 v[14:15], v[6:7], v[6:7]
	v_add_f32_e32 v12, v12, v13
	v_add_f32_e32 v12, v14, v12
	v_pk_mul_f32 v[16:17], v[10:11], v[10:11]
	v_add_f32_e32 v12, v15, v12
	v_add_f32_e32 v12, v16, v12
	v_pk_mul_f32 v[18:19], v[8:9], v[8:9]
	v_add_f32_e32 v12, v17, v12
	v_add_f32_e32 v12, v18, v12
	v_add_f32_e32 v12, v19, v12
	s_nop 1
	v_add_f32_dpp v12, v12, v12 quad_perm:[1,0,3,2] row_mask:0xf bank_mask:0xf
	v_readlane_b32 s4, v254, 56
	v_readlane_b32 s5, v254, 57
	s_waitcnt lgkmcnt(0)
	s_nop 1
	v_add_f32_dpp v12, v12, v12 quad_perm:[2,3,0,1] row_mask:0xf bank_mask:0xf
	s_nop 1
	v_add_f32_dpp v12, v12, v12 row_half_mirror row_mask:0xf bank_mask:0xf
	s_nop 1
	v_add_f32_dpp v12, v12, v12 row_mirror row_mask:0xf bank_mask:0xf
	v_add_f32_e32 v12, 0x358637bd, v12
	v_rsq_f32_e32 v12, v12
	s_nop 0
	v_mul_f32_e32 v13, 0x3db504f3, v12
	v_cndmask_b32_e64 v12, v12, v13, s[4:5]
	v_pk_mul_f32 v[8:9], v[8:9], v[12:13] op_sel_hi:[1,0]
	v_pk_mul_f32 v[10:11], v[10:11], v[12:13] op_sel_hi:[1,0]
	v_pk_mul_f32 v[6:7], v[6:7], v[12:13] op_sel_hi:[1,0]
	v_pk_mul_f32 v[32:33], v[32:33], v[12:13] op_sel_hi:[1,0]

; __device__ __forceinline__ float bflo(unsigned w) { return __uint_as_float(w << 16); }
; __device__ __forceinline__ float bfhi(unsigned w) { return __uint_as_float(w & 0xffff0000u); }
; __device__ __forceinline__ float bflo(unsigned w) { return __uint_as_float(w << 16); }
; __device__ __forceinline__ float bfhi(unsigned w) { return __uint_as_float(w & 0xffff0000u); }
; #define conv_w INP(4)
; __device__ __forceinline__ void gdn_prep_unit(LAS unsigned char* lds, unsigned char* ws, const float* conv_w, const float* a_log, const float* dt_bias,
;                                               int l, int Tp, int ci, int h, int nci, int nh, unsigned& pre_ba, int tid, int wave, int lane) {
;     ...
;             const float* cw = conv_w + (size_t)l * 3 * 3072 + chan;
;             const f32x4 w0a = *(const f32x4*)cw, w0b = *(const f32x4*)(cw + 4), w1a = *(const f32x4*)(cw + 3072), w1b = *(const f32x4*)(cw + 3072 + 4), w2a = *(const f32x4*)(cw + 6144), w2b = *(const f32x4*)(cw + 6144 + 4);
;             const float w0[8] = {w0a.x, w0a.y, w0a.z, w0a.w, w0b.x, w0b.y, w0b.z, w0b.w}, w1[8] = {w1a.x, w1a.y, w1a.z, w1a.w, w1b.x, w1b.y, w1b.z, w1b.w}, w2[8] = {w2a.x, w2a.y, w2a.z, w2a.w, w2b.x, w2b.y, w2b.z, w2b.w};
;             const float a0[8] = {bflo(x0.x), bfhi(x0.x), bflo(x0.y), bfhi(x0.y), bflo(x0.z), bfhi(x0.z), bflo(x0.w), bfhi(x0.w)};
;             const float a1[8] = {bflo(x1.x), bfhi(x1.x), bflo(x1.y), bfhi(x1.y), bflo(x1.z), bfhi(x1.z), bflo(x1.w), bfhi(x1.w)};
;             const float a2[8] = {bflo(x2.x), bfhi(x2.x), bflo(x2.y), bfhi(x2.y), bflo(x2.z), bfhi(x2.z), bflo(x2.w), bfhi(x2.w)};
;             float y[8]; float ss = 0.f;
; #pragma unroll
;             for (int e = 0; e < 8; ++e) { const float a = a0[e] * w0[e] + a1[e] * w1[e] + a2[e] * w2[e]; y[e] = a * __builtin_amdgcn_rcpf(1.0f + __expf(-a)); ss += y[e] * y[e]; }
;             if (mat < 2) {
;                 ss += xshfl<1>(ss); ss += xshfl<2>(ss); ss += xshfl<4>(ss); ss += xshfl<8>(ss);
;                 float rs = __builtin_amdgcn_rsqf(ss + NORM_EPS); if (mat == 0) rs *= 0.08838834764831845f;
; #pragma unroll
;                 for (int e = 0; e < 8; ++e) y[e] *= rs;
;             }
.LBB0_344:
	s_or_b64 exec, exec, s[90:91]
	v_lshl_add_u64 v[26:27], v[10:11], 2, s[44:45]
	s_mov_b64 s[4:5], 0x3000
	v_add_co_u32_e32 v12, vcc, 0x3000, v26
	v_lshl_add_u64 v[10:11], v[26:27], 0, s[4:5]
	s_nop 0
	v_addc_co_u32_e32 v13, vcc, 0, v27, vcc
	s_mov_b64 s[4:5], 0x6000
	global_load_dwordx4 v[22:25], v[26:27], off offset:16
	global_load_dwordx4 v[212:215], v[26:27], off
	global_load_dwordx4 v[216:219], v[12:13], off
	s_nop 0
	global_load_dwordx4 v[10:13], v[10:11], off offset:16
	v_lshl_add_u64 v[28:29], v[26:27], 0, s[4:5]
	v_add_co_u32_e32 v26, vcc, s3, v26
	s_waitcnt vmcnt(4)
	v_lshlrev_b32_e32 v36, 16, v6
	v_addc_co_u32_e32 v27, vcc, 0, v27, vcc
	global_load_dwordx4 v[236:239], v[26:27], off
	s_nop 0
	global_load_dwordx4 v[26:29], v[28:29], off offset:16
	v_and_b32_e32 v37, 0xffff0000, v6
	v_lshlrev_b32_e32 v32, 16, v14
	v_and_b32_e32 v33, 0xffff0000, v14
	v_lshlrev_b32_e32 v196, 16, v18
	v_and_b32_e32 v197, 0xffff0000, v18
	v_lshlrev_b32_e32 v14, 16, v15
	v_and_b32_e32 v15, 0xffff0000, v15
	v_lshlrev_b32_e32 v18, 16, v19
	v_and_b32_e32 v19, 0xffff0000, v19
	v_lshlrev_b32_e32 v211, 16, v21
	v_lshlrev_b32_e32 v35, 16, v17
	v_readlane_b32 s4, v255, 2
	v_readlane_b32 s5, v255, 3
	s_waitcnt vmcnt(3)
	v_pk_mul_f32 v[36:37], v[216:217], v[36:37]
	s_nop 0
	v_pk_fma_f32 v[32:33], v[212:213], v[32:33], v[36:37]
	s_waitcnt vmcnt(1)
	v_pk_fma_f32 v[32:33], v[236:237], v[196:197], v[32:33]
	s_nop 0
	v_mul_f32_e32 v6, 0xbfb8aa3b, v32
	v_exp_f32_e32 v6, v6
	s_nop 0
	v_add_f32_e32 v6, 1.0, v6
	v_rcp_f32_e32 v36, v6
	v_mul_f32_e32 v6, 0xbfb8aa3b, v33
	v_exp_f32_e32 v6, v6
	s_nop 0
	v_add_f32_e32 v6, 1.0, v6
	v_rcp_f32_e32 v37, v6
	v_lshlrev_b32_e32 v6, 16, v7
	v_and_b32_e32 v7, 0xffff0000, v7
	v_pk_mul_f32 v[6:7], v[218:219], v[6:7]
	v_pk_mul_f32 v[32:33], v[32:33], v[36:37]
	v_pk_fma_f32 v[6:7], v[214:215], v[14:15], v[6:7]
	v_and_b32_e32 v37, 0xffff0000, v20
	v_pk_fma_f32 v[6:7], v[238:239], v[18:19], v[6:7]
	v_and_b32_e32 v19, 0xffff0000, v8
	v_mul_f32_e32 v14, 0xbfb8aa3b, v6
	v_mul_f32_e32 v15, 0xbfb8aa3b, v7
	v_exp_f32_e32 v14, v14
	v_exp_f32_e32 v15, v15
	v_lshlrev_b32_e32 v18, 16, v8
	v_pk_mul_f32 v[10:11], v[10:11], v[18:19]
	v_add_f32_e32 v14, 1.0, v14
	v_add_f32_e32 v15, 1.0, v15
	v_rcp_f32_e32 v14, v14
	v_rcp_f32_e32 v15, v15
	v_lshlrev_b32_e32 v36, 16, v20
	v_and_b32_e32 v19, 0xffff0000, v21
	v_and_b32_e32 v18, 0xffff0000, v17
	v_pk_mul_f32 v[6:7], v[6:7], v[14:15]
	v_and_b32_e32 v15, 0xffff0000, v16
	v_lshlrev_b32_e32 v14, 16, v16
	v_pk_fma_f32 v[10:11], v[22:23], v[14:15], v[10:11]
	s_waitcnt vmcnt(0)
	v_pk_fma_f32 v[10:11], v[26:27], v[36:37], v[10:11]
	s_nop 0
	v_mul_f32_e32 v8, 0xbfb8aa3b, v10
	v_exp_f32_e32 v8, v8
	s_nop 0
	v_add_f32_e32 v8, 1.0, v8
	v_rcp_f32_e32 v14, v8
	v_mul_f32_e32 v8, 0xbfb8aa3b, v11
	v_exp_f32_e32 v8, v8
	s_nop 0
	v_add_f32_e32 v8, 1.0, v8
	v_rcp_f32_e32 v15, v8
	v_mul_f32_e32 v8, v24, v35
	v_pk_mul_f32 v[10:11], v[10:11], v[14:15]
	v_mul_f32_e32 v14, v28, v211
	v_mov_b32_e32 v28, v25
	v_pk_mul_f32 v[16:17], v[28:29], v[18:19]
	v_and_b32_e32 v19, 0xffff0000, v9
	v_lshlrev_b32_e32 v18, 16, v9
	v_mov_b32_e32 v9, v16
	v_pk_fma_f32 v[8:9], v[12:13], v[18:19], v[8:9]
	v_mov_b32_e32 v15, v17
	v_pk_add_f32 v[8:9], v[8:9], v[14:15]
	s_nop 0
	v_mul_f32_e32 v12, 0xbfb8aa3b, v8
	v_mul_f32_e32 v13, 0xbfb8aa3b, v9
	v_exp_f32_e32 v12, v12
	v_exp_f32_e32 v13, v13
	v_add_f32_e32 v12, 1.0, v12
	v_add_f32_e32 v13, 1.0, v13
	v_rcp_f32_e32 v12, v12
	v_rcp_f32_e32 v13, v13
	s_nop 0
	v_pk_mul_f32 v[8:9], v[8:9], v[12:13]
	s_and_saveexec_b64 s[90:91], s[4:5]
	s_cbranch_execz .LBB0_346
	v_pk_mul_f32 v[12:13], v[32:33], v[32:33]
	v_pk_mul_f32 v[14:15], v[6:7], v[6:7]
	v_add_f32_e32 v12, v12, v13
	v_add_f32_e32 v12, v14, v12
	v_pk_mul_f32 v[16:17], v[10:11], v[10:11]
	v_add_f32_e32 v12, v15, v12
	v_add_f32_e32 v12, v16, v12
	v_pk_mul_f32 v[18:19], v[8:9], v[8:9]
	v_add_f32_e32 v12, v17, v12
	v_add_f32_e32 v12, v18, v12
	v_add_f32_e32 v12, v19, v12
	s_nop 1
	v_add_f32_dpp v12, v12, v12 quad_perm:[1,0,3,2] row_mask:0xf bank_mask:0xf
	v_readlane_b32 s4, v255, 4
	v_readlane_b32 s5, v255, 5
	s_waitcnt lgkmcnt(0)
	s_nop 1
	v_add_f32_dpp v12, v12, v12 quad_perm:[2,3,0,1] row_mask:0xf bank_mask:0xf
	s_nop 1
	v_add_f32_dpp v12, v12, v12 row_half_mirror row_mask:0xf bank_mask:0xf
	s_nop 1
	v_add_f32_dpp v12, v12, v12 row_mirror row_mask:0xf bank_mask:0xf
	v_add_f32_e32 v12, 0x358637bd, v12
	v_rsq_f32_e32 v12, v12
	s_nop 0
	v_mul_f32_e32 v13, 0x3db504f3, v12
	v_cndmask_b32_e64 v12, v12, v13, s[4:5]
	v_pk_mul_f32 v[8:9], v[8:9], v[12:13] op_sel_hi:[1,0]
	v_pk_mul_f32 v[10:11], v[10:11], v[12:13] op_sel_hi:[1,0]
	v_pk_mul_f32 v[6:7], v[6:7], v[12:13] op_sel_hi:[1,0]
	v_pk_mul_f32 v[32:33], v[32:33], v[12:13] op_sel_hi:[1,0]

; __device__ __forceinline__ float bflo(unsigned w) { return __uint_as_float(w << 16); }
; __device__ __forceinline__ float bfhi(unsigned w) { return __uint_as_float(w & 0xffff0000u); }
; __device__ __forceinline__ float bflo(unsigned w) { return __uint_as_float(w << 16); }
; __device__ __forceinline__ float bfhi(unsigned w) { return __uint_as_float(w & 0xffff0000u); }
; #define conv_w INP(4)
; __device__ __forceinline__ void gdn_prep_unit(LAS unsigned char* lds, unsigned char* ws, const float* conv_w, const float* a_log, const float* dt_bias,
;                                               int l, int Tp, int ci, int h, int nci, int nh, unsigned& pre_ba, int tid, int wave, int lane) {
;     ...
;             const float* cw = conv_w + (size_t)l * 3 * 3072 + chan;
;             const f32x4 w0a = *(const f32x4*)cw, w0b = *(const f32x4*)(cw + 4), w1a = *(const f32x4*)(cw + 3072), w1b = *(const f32x4*)(cw + 3072 + 4), w2a = *(const f32x4*)(cw + 6144), w2b = *(const f32x4*)(cw + 6144 + 4);
;             const float w0[8] = {w0a.x, w0a.y, w0a.z, w0a.w, w0b.x, w0b.y, w0b.z, w0b.w}, w1[8] = {w1a.x, w1a.y, w1a.z, w1a.w, w1b.x, w1b.y, w1b.z, w1b.w}, w2[8] = {w2a.x, w2a.y, w2a.z, w2a.w, w2b.x, w2b.y, w2b.z, w2b.w};
;             const float a0[8] = {bflo(x0.x), bfhi(x0.x), bflo(x0.y), bfhi(x0.y), bflo(x0.z), bfhi(x0.z), bflo(x0.w), bfhi(x0.w)};
;             const float a1[8] = {bflo(x1.x), bfhi(x1.x), bflo(x1.y), bfhi(x1.y), bflo(x1.z), bfhi(x1.z), bflo(x1.w), bfhi(x1.w)};
;             const float a2[8] = {bflo(x2.x), bfhi(x2.x), bflo(x2.y), bfhi(x2.y), bflo(x2.z), bfhi(x2.z), bflo(x2.w), bfhi(x2.w)};
;             float y[8]; float ss = 0.f;
; #pragma unroll
;             for (int e = 0; e < 8; ++e) { const float a = a0[e] * w0[e] + a1[e] * w1[e] + a2[e] * w2[e]; y[e] = a * __builtin_amdgcn_rcpf(1.0f + __expf(-a)); ss += y[e] * y[e]; }
;             if (mat < 2) {
;                 ss += xshfl<1>(ss); ss += xshfl<2>(ss); ss += xshfl<4>(ss); ss += xshfl<8>(ss);
;                 float rs = __builtin_amdgcn_rsqf(ss + NORM_EPS); if (mat == 0) rs *= 0.08838834764831845f;
; #pragma unroll
;                 for (int e = 0; e < 8; ++e) y[e] *= rs;
;             }
.LBB0_358:
	s_or_b64 exec, exec, s[90:91]
	v_lshl_add_u64 v[26:27], v[10:11], 2, s[44:45]
	s_mov_b64 s[4:5], 0x3000
	v_add_co_u32_e32 v12, vcc, 0x3000, v26
	v_lshl_add_u64 v[10:11], v[26:27], 0, s[4:5]
	s_nop 0
	v_addc_co_u32_e32 v13, vcc, 0, v27, vcc
	s_mov_b64 s[4:5], 0x6000
	global_load_dwordx4 v[22:25], v[26:27], off offset:16
	global_load_dwordx4 v[212:215], v[26:27], off
	global_load_dwordx4 v[216:219], v[12:13], off
	s_nop 0
	global_load_dwordx4 v[10:13], v[10:11], off offset:16
	v_lshl_add_u64 v[28:29], v[26:27], 0, s[4:5]
	v_add_co_u32_e32 v26, vcc, s3, v26
	s_waitcnt vmcnt(4)
	v_lshlrev_b32_e32 v36, 16, v6
	v_addc_co_u32_e32 v27, vcc, 0, v27, vcc
	global_load_dwordx4 v[236:239], v[26:27], off
	s_nop 0
	global_load_dwordx4 v[26:29], v[28:29], off offset:16
	v_and_b32_e32 v37, 0xffff0000, v6
	v_lshlrev_b32_e32 v32, 16, v14
	v_and_b32_e32 v33, 0xffff0000, v14
	v_lshlrev_b32_e32 v196, 16, v18
	v_and_b32_e32 v197, 0xffff0000, v18
	v_lshlrev_b32_e32 v14, 16, v15
	v_and_b32_e32 v15, 0xffff0000, v15
	v_lshlrev_b32_e32 v18, 16, v19
	v_and_b32_e32 v19, 0xffff0000, v19
	v_lshlrev_b32_e32 v211, 16, v21
	v_lshlrev_b32_e32 v35, 16, v17
	s_waitcnt vmcnt(3)
	v_pk_mul_f32 v[36:37], v[216:217], v[36:37]
	s_nop 0
	v_pk_fma_f32 v[32:33], v[212:213], v[32:33], v[36:37]
	s_waitcnt vmcnt(1)
	v_pk_fma_f32 v[32:33], v[236:237], v[196:197], v[32:33]
	s_nop 0
	v_mul_f32_e32 v6, 0xbfb8aa3b, v32
	v_exp_f32_e32 v6, v6
	s_nop 0
	v_add_f32_e32 v6, 1.0, v6
	v_rcp_f32_e32 v36, v6
	v_mul_f32_e32 v6, 0xbfb8aa3b, v33
	v_exp_f32_e32 v6, v6
	s_nop 0
	v_add_f32_e32 v6, 1.0, v6
	v_rcp_f32_e32 v37, v6
	v_lshlrev_b32_e32 v6, 16, v7
	v_and_b32_e32 v7, 0xffff0000, v7
	v_pk_mul_f32 v[6:7], v[218:219], v[6:7]
	v_pk_mul_f32 v[32:33], v[32:33], v[36:37]
	v_pk_fma_f32 v[6:7], v[214:215], v[14:15], v[6:7]
	v_and_b32_e32 v37, 0xffff0000, v20
	v_pk_fma_f32 v[6:7], v[238:239], v[18:19], v[6:7]
	v_and_b32_e32 v19, 0xffff0000, v8
	v_mul_f32_e32 v14, 0xbfb8aa3b, v6
	v_mul_f32_e32 v15, 0xbfb8aa3b, v7
	v_exp_f32_e32 v14, v14
	v_exp_f32_e32 v15, v15
	v_lshlrev_b32_e32 v18, 16, v8
	v_pk_mul_f32 v[10:11], v[10:11], v[18:19]
	v_add_f32_e32 v14, 1.0, v14
	v_add_f32_e32 v15, 1.0, v15
	v_rcp_f32_e32 v14, v14
	v_rcp_f32_e32 v15, v15
	v_lshlrev_b32_e32 v36, 16, v20
	v_and_b32_e32 v19, 0xffff0000, v21
	v_and_b32_e32 v18, 0xffff0000, v17
	v_pk_mul_f32 v[6:7], v[6:7], v[14:15]
	v_and_b32_e32 v15, 0xffff0000, v16
	v_lshlrev_b32_e32 v14, 16, v16
	v_pk_fma_f32 v[10:11], v[22:23], v[14:15], v[10:11]
	s_waitcnt vmcnt(0)
	v_pk_fma_f32 v[10:11], v[26:27], v[36:37], v[10:11]
	s_nop 0
	v_mul_f32_e32 v8, 0xbfb8aa3b, v10
	v_exp_f32_e32 v8, v8
	s_nop 0
	v_add_f32_e32 v8, 1.0, v8
	v_rcp_f32_e32 v14, v8
	v_mul_f32_e32 v8, 0xbfb8aa3b, v11
	v_exp_f32_e32 v8, v8
	s_nop 0
	v_add_f32_e32 v8, 1.0, v8
	v_rcp_f32_e32 v15, v8
	v_mul_f32_e32 v8, v24, v35
	v_pk_mul_f32 v[10:11], v[10:11], v[14:15]
	v_mul_f32_e32 v14, v28, v211
	v_mov_b32_e32 v28, v25
	v_pk_mul_f32 v[16:17], v[28:29], v[18:19]
	v_and_b32_e32 v19, 0xffff0000, v9
	v_lshlrev_b32_e32 v18, 16, v9
	v_mov_b32_e32 v9, v16
	v_pk_fma_f32 v[8:9], v[12:13], v[18:19], v[8:9]
	v_mov_b32_e32 v15, v17
	v_pk_add_f32 v[8:9], v[8:9], v[14:15]
	s_nop 0
	v_mul_f32_e32 v12, 0xbfb8aa3b, v8
	v_mul_f32_e32 v13, 0xbfb8aa3b, v9
	v_exp_f32_e32 v12, v12
	v_exp_f32_e32 v13, v13
	v_add_f32_e32 v12, 1.0, v12
	v_add_f32_e32 v13, 1.0, v13
	v_rcp_f32_e32 v12, v12
	v_rcp_f32_e32 v13, v13
	s_nop 0
	v_pk_mul_f32 v[8:9], v[8:9], v[12:13]
	s_mov_b64 s[90:91], exec
	v_readlane_b32 s4, v255, 10
	v_readlane_b32 s5, v255, 11
	s_and_b64 s[4:5], s[90:91], s[4:5]
	s_mov_b64 exec, s[4:5]
	s_cbranch_execz .LBB0_360
	v_pk_mul_f32 v[12:13], v[32:33], v[32:33]
	v_pk_mul_f32 v[14:15], v[6:7], v[6:7]
	v_add_f32_e32 v12, v12, v13
	v_add_f32_e32 v12, v14, v12
	v_pk_mul_f32 v[16:17], v[10:11], v[10:11]
	v_add_f32_e32 v12, v15, v12
	v_add_f32_e32 v12, v16, v12
	v_pk_mul_f32 v[18:19], v[8:9], v[8:9]
	v_add_f32_e32 v12, v17, v12
	v_add_f32_e32 v12, v18, v12
	v_add_f32_e32 v12, v19, v12
	s_nop 1
	v_add_f32_dpp v12, v12, v12 quad_perm:[1,0,3,2] row_mask:0xf bank_mask:0xf
	v_readlane_b32 s4, v255, 12
	v_readlane_b32 s5, v255, 13
	s_waitcnt lgkmcnt(0)
	s_nop 1
	v_add_f32_dpp v12, v12, v12 quad_perm:[2,3,0,1] row_mask:0xf bank_mask:0xf
	s_nop 1
	v_add_f32_dpp v12, v12, v12 row_half_mirror row_mask:0xf bank_mask:0xf
	s_nop 1
	v_add_f32_dpp v12, v12, v12 row_mirror row_mask:0xf bank_mask:0xf
	v_add_f32_e32 v12, 0x358637bd, v12
	v_rsq_f32_e32 v12, v12
	s_nop 0
	v_mul_f32_e32 v13, 0x3db504f3, v12
	v_cndmask_b32_e64 v12, v12, v13, s[4:5]
	v_pk_mul_f32 v[8:9], v[8:9], v[12:13] op_sel_hi:[1,0]
	v_pk_mul_f32 v[10:11], v[10:11], v[12:13] op_sel_hi:[1,0]
	v_pk_mul_f32 v[6:7], v[6:7], v[12:13] op_sel_hi:[1,0]
	v_pk_mul_f32 v[32:33], v[32:33], v[12:13] op_sel_hi:[1,0]

; __device__ __forceinline__ float bflo(unsigned w) { return __uint_as_float(w << 16); }
; __device__ __forceinline__ float bfhi(unsigned w) { return __uint_as_float(w & 0xffff0000u); }
; __device__ __forceinline__ float bflo(unsigned w) { return __uint_as_float(w << 16); }
; __device__ __forceinline__ float bfhi(unsigned w) { return __uint_as_float(w & 0xffff0000u); }
; #define conv_w INP(4)
; __device__ __forceinline__ void gdn_prep_unit(LAS unsigned char* lds, unsigned char* ws, const float* conv_w, const float* a_log, const float* dt_bias,
;                                               int l, int Tp, int ci, int h, int nci, int nh, unsigned& pre_ba, int tid, int wave, int lane) {
;     ...
;             const float* cw = conv_w + (size_t)l * 3 * 3072 + chan;
;             const f32x4 w0a = *(const f32x4*)cw, w0b = *(const f32x4*)(cw + 4), w1a = *(const f32x4*)(cw + 3072), w1b = *(const f32x4*)(cw + 3072 + 4), w2a = *(const f32x4*)(cw + 6144), w2b = *(const f32x4*)(cw + 6144 + 4);
;             const float w0[8] = {w0a.x, w0a.y, w0a.z, w0a.w, w0b.x, w0b.y, w0b.z, w0b.w}, w1[8] = {w1a.x, w1a.y, w1a.z, w1a.w, w1b.x, w1b.y, w1b.z, w1b.w}, w2[8] = {w2a.x, w2a.y, w2a.z, w2a.w, w2b.x, w2b.y, w2b.z, w2b.w};
;             const float a0[8] = {bflo(x0.x), bfhi(x0.x), bflo(x0.y), bfhi(x0.y), bflo(x0.z), bfhi(x0.z), bflo(x0.w), bfhi(x0.w)};
;             const float a1[8] = {bflo(x1.x), bfhi(x1.x), bflo(x1.y), bfhi(x1.y), bflo(x1.z), bfhi(x1.z), bflo(x1.w), bfhi(x1.w)};
;             const float a2[8] = {bflo(x2.x), bfhi(x2.x), bflo(x2.y), bfhi(x2.y), bflo(x2.z), bfhi(x2.z), bflo(x2.w), bfhi(x2.w)};
;             float y[8]; float ss = 0.f;
; #pragma unroll
;             for (int e = 0; e < 8; ++e) { const float a = a0[e] * w0[e] + a1[e] * w1[e] + a2[e] * w2[e]; y[e] = a * __builtin_amdgcn_rcpf(1.0f + __expf(-a)); ss += y[e] * y[e]; }
;             if (mat < 2) {
;                 ss += xshfl<1>(ss); ss += xshfl<2>(ss); ss += xshfl<4>(ss); ss += xshfl<8>(ss);
;                 float rs = __builtin_amdgcn_rsqf(ss + NORM_EPS); if (mat == 0) rs *= 0.08838834764831845f;
; #pragma unroll
;                 for (int e = 0; e < 8; ++e) y[e] *= rs;
;             }
.LBB0_372:
	s_or_b64 exec, exec, s[90:91]
	v_lshl_add_u64 v[26:27], v[10:11], 2, s[44:45]
	s_mov_b64 s[4:5], 0x3000
	v_add_co_u32_e32 v12, vcc, 0x3000, v26
	v_lshl_add_u64 v[10:11], v[26:27], 0, s[4:5]
	s_nop 0
	v_addc_co_u32_e32 v13, vcc, 0, v27, vcc
	s_mov_b64 s[4:5], 0x6000
	global_load_dwordx4 v[22:25], v[26:27], off offset:16
	global_load_dwordx4 v[212:215], v[26:27], off
	global_load_dwordx4 v[216:219], v[12:13], off
	s_nop 0
	global_load_dwordx4 v[10:13], v[10:11], off offset:16
	v_lshl_add_u64 v[28:29], v[26:27], 0, s[4:5]
	v_add_co_u32_e32 v26, vcc, s3, v26
	s_waitcnt vmcnt(4)
	v_lshlrev_b32_e32 v36, 16, v6
	v_addc_co_u32_e32 v27, vcc, 0, v27, vcc
	global_load_dwordx4 v[236:239], v[26:27], off
	s_nop 0
	global_load_dwordx4 v[26:29], v[28:29], off offset:16
	v_and_b32_e32 v37, 0xffff0000, v6
	v_lshlrev_b32_e32 v32, 16, v14
	v_and_b32_e32 v33, 0xffff0000, v14
	v_lshlrev_b32_e32 v196, 16, v18
	v_and_b32_e32 v197, 0xffff0000, v18
	v_lshlrev_b32_e32 v14, 16, v15
	v_and_b32_e32 v15, 0xffff0000, v15
	v_lshlrev_b32_e32 v18, 16, v19
	v_and_b32_e32 v19, 0xffff0000, v19
	v_lshlrev_b32_e32 v211, 16, v21
	v_lshlrev_b32_e32 v35, 16, v17
	s_waitcnt vmcnt(3)
	v_pk_mul_f32 v[36:37], v[216:217], v[36:37]
	s_nop 0
	v_pk_fma_f32 v[32:33], v[212:213], v[32:33], v[36:37]
	s_waitcnt vmcnt(1)
	v_pk_fma_f32 v[32:33], v[236:237], v[196:197], v[32:33]
	s_nop 0
	v_mul_f32_e32 v6, 0xbfb8aa3b, v32
	v_exp_f32_e32 v6, v6
	s_nop 0
	v_add_f32_e32 v6, 1.0, v6
	v_rcp_f32_e32 v36, v6
	v_mul_f32_e32 v6, 0xbfb8aa3b, v33
	v_exp_f32_e32 v6, v6
	s_nop 0
	v_add_f32_e32 v6, 1.0, v6
	v_rcp_f32_e32 v37, v6
	v_lshlrev_b32_e32 v6, 16, v7
	v_and_b32_e32 v7, 0xffff0000, v7
	v_pk_mul_f32 v[6:7], v[218:219], v[6:7]
	v_pk_mul_f32 v[32:33], v[32:33], v[36:37]
	v_pk_fma_f32 v[6:7], v[214:215], v[14:15], v[6:7]
	v_and_b32_e32 v37, 0xffff0000, v20
	v_pk_fma_f32 v[6:7], v[238:239], v[18:19], v[6:7]
	v_and_b32_e32 v19, 0xffff0000, v8
	v_mul_f32_e32 v14, 0xbfb8aa3b, v6
	v_mul_f32_e32 v15, 0xbfb8aa3b, v7
	v_exp_f32_e32 v14, v14
	v_exp_f32_e32 v15, v15
	v_lshlrev_b32_e32 v18, 16, v8
	v_pk_mul_f32 v[10:11], v[10:11], v[18:19]
	v_add_f32_e32 v14, 1.0, v14
	v_add_f32_e32 v15, 1.0, v15
	v_rcp_f32_e32 v14, v14
	v_rcp_f32_e32 v15, v15
	v_lshlrev_b32_e32 v36, 16, v20
	v_and_b32_e32 v19, 0xffff0000, v21
	v_and_b32_e32 v18, 0xffff0000, v17
	v_pk_mul_f32 v[6:7], v[6:7], v[14:15]
	v_and_b32_e32 v15, 0xffff0000, v16
	v_lshlrev_b32_e32 v14, 16, v16
	v_pk_fma_f32 v[10:11], v[22:23], v[14:15], v[10:11]
	s_waitcnt vmcnt(0)
	v_pk_fma_f32 v[10:11], v[26:27], v[36:37], v[10:11]
	s_nop 0
	v_mul_f32_e32 v8, 0xbfb8aa3b, v10
	v_exp_f32_e32 v8, v8
	s_nop 0
	v_add_f32_e32 v8, 1.0, v8
	v_rcp_f32_e32 v14, v8
	v_mul_f32_e32 v8, 0xbfb8aa3b, v11
	v_exp_f32_e32 v8, v8
	s_nop 0
	v_add_f32_e32 v8, 1.0, v8
	v_rcp_f32_e32 v15, v8
	v_mul_f32_e32 v8, v24, v35
	v_pk_mul_f32 v[10:11], v[10:11], v[14:15]
	v_mul_f32_e32 v14, v28, v211
	v_mov_b32_e32 v28, v25
	v_pk_mul_f32 v[16:17], v[28:29], v[18:19]
	v_and_b32_e32 v19, 0xffff0000, v9
	v_lshlrev_b32_e32 v18, 16, v9
	v_mov_b32_e32 v9, v16
	v_pk_fma_f32 v[8:9], v[12:13], v[18:19], v[8:9]
	v_mov_b32_e32 v15, v17
	v_pk_add_f32 v[8:9], v[8:9], v[14:15]
	s_nop 0
	v_mul_f32_e32 v12, 0xbfb8aa3b, v8
	v_mul_f32_e32 v13, 0xbfb8aa3b, v9
	v_exp_f32_e32 v12, v12
	v_exp_f32_e32 v13, v13
	v_add_f32_e32 v12, 1.0, v12
	v_add_f32_e32 v13, 1.0, v13
	v_rcp_f32_e32 v12, v12
	v_rcp_f32_e32 v13, v13
	s_nop 0
	v_pk_mul_f32 v[8:9], v[8:9], v[12:13]
	s_mov_b64 s[90:91], exec
	v_readlane_b32 s4, v255, 22
	v_readlane_b32 s5, v255, 23
	s_and_b64 s[4:5], s[90:91], s[4:5]
	s_mov_b64 exec, s[4:5]
	s_cbranch_execz .LBB0_374
	v_pk_mul_f32 v[12:13], v[32:33], v[32:33]
	v_pk_mul_f32 v[14:15], v[6:7], v[6:7]
	v_add_f32_e32 v12, v12, v13
	v_add_f32_e32 v12, v14, v12
	v_pk_mul_f32 v[16:17], v[10:11], v[10:11]
	v_add_f32_e32 v12, v15, v12
	v_add_f32_e32 v12, v16, v12
	v_pk_mul_f32 v[18:19], v[8:9], v[8:9]
	v_add_f32_e32 v12, v17, v12
	v_add_f32_e32 v12, v18, v12
	v_add_f32_e32 v12, v19, v12
	s_nop 1
	v_add_f32_dpp v12, v12, v12 quad_perm:[1,0,3,2] row_mask:0xf bank_mask:0xf
	v_readlane_b32 s4, v255, 24
	v_readlane_b32 s5, v255, 25
	s_waitcnt lgkmcnt(0)
	s_nop 1
	v_add_f32_dpp v12, v12, v12 quad_perm:[2,3,0,1] row_mask:0xf bank_mask:0xf
	s_nop 1
	v_add_f32_dpp v12, v12, v12 row_half_mirror row_mask:0xf bank_mask:0xf
	s_nop 1
	v_add_f32_dpp v12, v12, v12 row_mirror row_mask:0xf bank_mask:0xf
	v_add_f32_e32 v12, 0x358637bd, v12
	v_rsq_f32_e32 v12, v12
	s_nop 0
	v_mul_f32_e32 v13, 0x3db504f3, v12
	v_cndmask_b32_e64 v12, v12, v13, s[4:5]
	v_pk_mul_f32 v[8:9], v[8:9], v[12:13] op_sel_hi:[1,0]
	v_pk_mul_f32 v[10:11], v[10:11], v[12:13] op_sel_hi:[1,0]
	v_pk_mul_f32 v[6:7], v[6:7], v[12:13] op_sel_hi:[1,0]
	v_pk_mul_f32 v[32:33], v[32:33], v[12:13] op_sel_hi:[1,0]

; __device__ __forceinline__ float bflo(unsigned w) { return __uint_as_float(w << 16); }
; __device__ __forceinline__ float bfhi(unsigned w) { return __uint_as_float(w & 0xffff0000u); }
; __device__ __forceinline__ float bflo(unsigned w) { return __uint_as_float(w << 16); }
; __device__ __forceinline__ float bfhi(unsigned w) { return __uint_as_float(w & 0xffff0000u); }
; #define conv_w INP(4)
; __device__ __forceinline__ void gdn_prep_unit(LAS unsigned char* lds, unsigned char* ws, const float* conv_w, const float* a_log, const float* dt_bias,
;                                               int l, int Tp, int ci, int h, int nci, int nh, unsigned& pre_ba, int tid, int wave, int lane) {
;     ...
;             const float* cw = conv_w + (size_t)l * 3 * 3072 + chan;
;             const f32x4 w0a = *(const f32x4*)cw, w0b = *(const f32x4*)(cw + 4), w1a = *(const f32x4*)(cw + 3072), w1b = *(const f32x4*)(cw + 3072 + 4), w2a = *(const f32x4*)(cw + 6144), w2b = *(const f32x4*)(cw + 6144 + 4);
;             const float w0[8] = {w0a.x, w0a.y, w0a.z, w0a.w, w0b.x, w0b.y, w0b.z, w0b.w}, w1[8] = {w1a.x, w1a.y, w1a.z, w1a.w, w1b.x, w1b.y, w1b.z, w1b.w}, w2[8] = {w2a.x, w2a.y, w2a.z, w2a.w, w2b.x, w2b.y, w2b.z, w2b.w};
;             const float a0[8] = {bflo(x0.x), bfhi(x0.x), bflo(x0.y), bfhi(x0.y), bflo(x0.z), bfhi(x0.z), bflo(x0.w), bfhi(x0.w)};
;             const float a1[8] = {bflo(x1.x), bfhi(x1.x), bflo(x1.y), bfhi(x1.y), bflo(x1.z), bfhi(x1.z), bflo(x1.w), bfhi(x1.w)};
;             const float a2[8] = {bflo(x2.x), bfhi(x2.x), bflo(x2.y), bfhi(x2.y), bflo(x2.z), bfhi(x2.z), bflo(x2.w), bfhi(x2.w)};
;             float y[8]; float ss = 0.f;
; #pragma unroll
;             for (int e = 0; e < 8; ++e) { const float a = a0[e] * w0[e] + a1[e] * w1[e] + a2[e] * w2[e]; y[e] = a * __builtin_amdgcn_rcpf(1.0f + __expf(-a)); ss += y[e] * y[e]; }
;             if (mat < 2) {
;                 ss += xshfl<1>(ss); ss += xshfl<2>(ss); ss += xshfl<4>(ss); ss += xshfl<8>(ss);
;                 float rs = __builtin_amdgcn_rsqf(ss + NORM_EPS); if (mat == 0) rs *= 0.08838834764831845f;
; #pragma unroll
;                 for (int e = 0; e < 8; ++e) y[e] *= rs;
;             }
.LBB0_386:
	s_or_b64 exec, exec, s[84:85]
	v_lshl_add_u64 v[26:27], v[10:11], 2, s[44:45]
	s_mov_b64 s[4:5], 0x3000
	v_add_co_u32_e32 v12, vcc, 0x3000, v26
	v_lshl_add_u64 v[10:11], v[26:27], 0, s[4:5]
	s_nop 0
	v_addc_co_u32_e32 v13, vcc, 0, v27, vcc
	s_mov_b64 s[4:5], 0x6000
	global_load_dwordx4 v[22:25], v[26:27], off offset:16
	global_load_dwordx4 v[30:33], v[26:27], off
	global_load_dwordx4 v[212:215], v[12:13], off
	s_nop 0
	global_load_dwordx4 v[10:13], v[10:11], off offset:16
	v_lshl_add_u64 v[28:29], v[26:27], 0, s[4:5]
	v_add_co_u32_e32 v26, vcc, s3, v26
	s_waitcnt vmcnt(4)
	v_lshlrev_b32_e32 v196, 16, v6
	v_addc_co_u32_e32 v27, vcc, 0, v27, vcc
	global_load_dwordx4 v[216:219], v[26:27], off
	s_nop 0
	global_load_dwordx4 v[26:29], v[28:29], off offset:16
	v_and_b32_e32 v197, 0xffff0000, v6
	v_lshlrev_b32_e32 v36, 16, v14
	v_and_b32_e32 v37, 0xffff0000, v14
	v_lshlrev_b32_e32 v228, 16, v18
	v_and_b32_e32 v229, 0xffff0000, v18
	v_lshlrev_b32_e32 v14, 16, v15
	v_and_b32_e32 v15, 0xffff0000, v15
	v_lshlrev_b32_e32 v18, 16, v19
	v_and_b32_e32 v19, 0xffff0000, v19
	v_lshlrev_b32_e32 v211, 16, v21
	v_lshlrev_b32_e32 v35, 16, v17
	s_waitcnt vmcnt(3)
	v_pk_mul_f32 v[196:197], v[212:213], v[196:197]
	s_nop 0
	v_pk_fma_f32 v[30:31], v[30:31], v[36:37], v[196:197]
	s_waitcnt vmcnt(1)
	v_pk_fma_f32 v[30:31], v[216:217], v[228:229], v[30:31]
	s_nop 0
	v_mul_f32_e32 v6, 0xbfb8aa3b, v30
	v_exp_f32_e32 v6, v6
	s_nop 0
	v_add_f32_e32 v6, 1.0, v6
	v_rcp_f32_e32 v36, v6
	v_mul_f32_e32 v6, 0xbfb8aa3b, v31
	v_exp_f32_e32 v6, v6
	s_nop 0
	v_add_f32_e32 v6, 1.0, v6
	v_rcp_f32_e32 v37, v6
	v_lshlrev_b32_e32 v6, 16, v7
	v_and_b32_e32 v7, 0xffff0000, v7
	v_pk_mul_f32 v[6:7], v[214:215], v[6:7]
	v_pk_mul_f32 v[30:31], v[30:31], v[36:37]
	v_pk_fma_f32 v[6:7], v[32:33], v[14:15], v[6:7]
	v_and_b32_e32 v33, 0xffff0000, v20
	v_pk_fma_f32 v[6:7], v[218:219], v[18:19], v[6:7]
	v_and_b32_e32 v19, 0xffff0000, v8
	v_mul_f32_e32 v14, 0xbfb8aa3b, v6
	v_mul_f32_e32 v15, 0xbfb8aa3b, v7
	v_exp_f32_e32 v14, v14
	v_exp_f32_e32 v15, v15
	v_lshlrev_b32_e32 v18, 16, v8
	v_pk_mul_f32 v[10:11], v[10:11], v[18:19]
	v_add_f32_e32 v14, 1.0, v14
	v_add_f32_e32 v15, 1.0, v15
	v_rcp_f32_e32 v14, v14
	v_rcp_f32_e32 v15, v15
	v_lshlrev_b32_e32 v32, 16, v20
	v_and_b32_e32 v19, 0xffff0000, v21
	v_and_b32_e32 v18, 0xffff0000, v17
	v_pk_mul_f32 v[6:7], v[6:7], v[14:15]
	v_and_b32_e32 v15, 0xffff0000, v16
	v_lshlrev_b32_e32 v14, 16, v16
	v_pk_fma_f32 v[10:11], v[22:23], v[14:15], v[10:11]
	s_waitcnt vmcnt(0)
	v_pk_fma_f32 v[10:11], v[26:27], v[32:33], v[10:11]
	s_nop 0
	v_mul_f32_e32 v8, 0xbfb8aa3b, v10
	v_exp_f32_e32 v8, v8
	s_nop 0
	v_add_f32_e32 v8, 1.0, v8
	v_rcp_f32_e32 v14, v8
	v_mul_f32_e32 v8, 0xbfb8aa3b, v11
	v_exp_f32_e32 v8, v8
	s_nop 0
	v_add_f32_e32 v8, 1.0, v8
	v_rcp_f32_e32 v15, v8
	v_mul_f32_e32 v8, v24, v35
	v_pk_mul_f32 v[10:11], v[10:11], v[14:15]
	v_mul_f32_e32 v14, v28, v211
	v_mov_b32_e32 v28, v25
	v_pk_mul_f32 v[16:17], v[28:29], v[18:19]
	v_and_b32_e32 v19, 0xffff0000, v9
	v_lshlrev_b32_e32 v18, 16, v9
	v_mov_b32_e32 v9, v16
	v_pk_fma_f32 v[8:9], v[12:13], v[18:19], v[8:9]
	v_mov_b32_e32 v15, v17
	v_pk_add_f32 v[8:9], v[8:9], v[14:15]
	s_nop 0
	v_mul_f32_e32 v12, 0xbfb8aa3b, v8
	v_mul_f32_e32 v13, 0xbfb8aa3b, v9
	v_exp_f32_e32 v12, v12
	v_exp_f32_e32 v13, v13
	v_add_f32_e32 v12, 1.0, v12
	v_add_f32_e32 v13, 1.0, v13
	v_rcp_f32_e32 v12, v12
	v_rcp_f32_e32 v13, v13
	s_nop 0
	v_pk_mul_f32 v[8:9], v[8:9], v[12:13]
	s_mov_b64 s[84:85], exec
	v_readlane_b32 s4, v255, 30
	v_readlane_b32 s5, v255, 31
	s_and_b64 s[4:5], s[84:85], s[4:5]
	s_mov_b64 exec, s[4:5]
	s_cbranch_execz .LBB0_388
	v_pk_mul_f32 v[12:13], v[30:31], v[30:31]
	v_pk_mul_f32 v[14:15], v[6:7], v[6:7]
	v_add_f32_e32 v12, v12, v13
	v_add_f32_e32 v12, v14, v12
	v_pk_mul_f32 v[16:17], v[10:11], v[10:11]
	v_add_f32_e32 v12, v15, v12
	v_add_f32_e32 v12, v16, v12
	v_pk_mul_f32 v[18:19], v[8:9], v[8:9]
	v_add_f32_e32 v12, v17, v12
	v_add_f32_e32 v12, v18, v12
	v_add_f32_e32 v12, v19, v12
	s_nop 1
	v_add_f32_dpp v12, v12, v12 quad_perm:[1,0,3,2] row_mask:0xf bank_mask:0xf
	v_readlane_b32 s4, v255, 32
	v_readlane_b32 s5, v255, 33
	s_waitcnt lgkmcnt(0)
	s_nop 1
	v_add_f32_dpp v12, v12, v12 quad_perm:[2,3,0,1] row_mask:0xf bank_mask:0xf
	s_nop 1
	v_add_f32_dpp v12, v12, v12 row_half_mirror row_mask:0xf bank_mask:0xf
	s_nop 1
	v_add_f32_dpp v12, v12, v12 row_mirror row_mask:0xf bank_mask:0xf
	v_add_f32_e32 v12, 0x358637bd, v12
	v_rsq_f32_e32 v12, v12
	s_nop 0
	v_mul_f32_e32 v13, 0x3db504f3, v12
	v_cndmask_b32_e64 v12, v12, v13, s[4:5]
	v_pk_mul_f32 v[8:9], v[8:9], v[12:13] op_sel_hi:[1,0]
	v_pk_mul_f32 v[10:11], v[10:11], v[12:13] op_sel_hi:[1,0]
	v_pk_mul_f32 v[6:7], v[6:7], v[12:13] op_sel_hi:[1,0]
	v_pk_mul_f32 v[30:31], v[30:31], v[12:13] op_sel_hi:[1,0]

; __device__ __forceinline__ float bflo(unsigned w) { return __uint_as_float(w << 16); }
; __device__ __forceinline__ float bfhi(unsigned w) { return __uint_as_float(w & 0xffff0000u); }
; __device__ __forceinline__ float bflo(unsigned w) { return __uint_as_float(w << 16); }
; __device__ __forceinline__ float bfhi(unsigned w) { return __uint_as_float(w & 0xffff0000u); }
; #define conv_w INP(4)
; __device__ __forceinline__ void gdn_prep_unit(LAS unsigned char* lds, unsigned char* ws, const float* conv_w, const float* a_log, const float* dt_bias,
;                                               int l, int Tp, int ci, int h, int nci, int nh, unsigned& pre_ba, int tid, int wave, int lane) {
;     ...
;             const float* cw = conv_w + (size_t)l * 3 * 3072 + chan;
;             const f32x4 w0a = *(const f32x4*)cw, w0b = *(const f32x4*)(cw + 4), w1a = *(const f32x4*)(cw + 3072), w1b = *(const f32x4*)(cw + 3072 + 4), w2a = *(const f32x4*)(cw + 6144), w2b = *(const f32x4*)(cw + 6144 + 4);
;             const float w0[8] = {w0a.x, w0a.y, w0a.z, w0a.w, w0b.x, w0b.y, w0b.z, w0b.w}, w1[8] = {w1a.x, w1a.y, w1a.z, w1a.w, w1b.x, w1b.y, w1b.z, w1b.w}, w2[8] = {w2a.x, w2a.y, w2a.z, w2a.w, w2b.x, w2b.y, w2b.z, w2b.w};
;             const float a0[8] = {bflo(x0.x), bfhi(x0.x), bflo(x0.y), bfhi(x0.y), bflo(x0.z), bfhi(x0.z), bflo(x0.w), bfhi(x0.w)};
;             const float a1[8] = {bflo(x1.x), bfhi(x1.x), bflo(x1.y), bfhi(x1.y), bflo(x1.z), bfhi(x1.z), bflo(x1.w), bfhi(x1.w)};
;             const float a2[8] = {bflo(x2.x), bfhi(x2.x), bflo(x2.y), bfhi(x2.y), bflo(x2.z), bfhi(x2.z), bflo(x2.w), bfhi(x2.w)};
;             float y[8]; float ss = 0.f;
; #pragma unroll
;             for (int e = 0; e < 8; ++e) { const float a = a0[e] * w0[e] + a1[e] * w1[e] + a2[e] * w2[e]; y[e] = a * __builtin_amdgcn_rcpf(1.0f + __expf(-a)); ss += y[e] * y[e]; }
;             if (mat < 2) {
;                 ss += xshfl<1>(ss); ss += xshfl<2>(ss); ss += xshfl<4>(ss); ss += xshfl<8>(ss);
;                 float rs = __builtin_amdgcn_rsqf(ss + NORM_EPS); if (mat == 0) rs *= 0.08838834764831845f;
; #pragma unroll
;                 for (int e = 0; e < 8; ++e) y[e] *= rs;
;             }
.LBB0_400:
	s_or_b64 exec, exec, s[26:27]
	v_lshl_add_u64 v[26:27], v[10:11], 2, s[44:45]
	s_mov_b64 s[4:5], 0x3000
	v_add_co_u32_e32 v12, vcc, 0x3000, v26
	v_lshl_add_u64 v[10:11], v[26:27], 0, s[4:5]
	s_nop 0
	v_addc_co_u32_e32 v13, vcc, 0, v27, vcc
	s_mov_b64 s[4:5], 0x6000
	global_load_dwordx4 v[22:25], v[26:27], off offset:16
	global_load_dwordx4 v[30:33], v[26:27], off
	global_load_dwordx4 v[34:37], v[12:13], off
	s_nop 0
	global_load_dwordx4 v[10:13], v[10:11], off offset:16
	v_lshl_add_u64 v[28:29], v[26:27], 0, s[4:5]
	v_add_co_u32_e32 v26, vcc, s3, v26
	s_waitcnt vmcnt(4)
	v_lshlrev_b32_e32 v216, 16, v6
	v_addc_co_u32_e32 v27, vcc, 0, v27, vcc
	global_load_dwordx4 v[212:215], v[26:27], off
	s_nop 0
	global_load_dwordx4 v[26:29], v[28:29], off offset:16
	v_and_b32_e32 v217, 0xffff0000, v6
	v_lshlrev_b32_e32 v196, 16, v14
	v_and_b32_e32 v197, 0xffff0000, v14
	v_lshlrev_b32_e32 v218, 16, v18
	v_and_b32_e32 v219, 0xffff0000, v18
	v_lshlrev_b32_e32 v14, 16, v15
	v_and_b32_e32 v15, 0xffff0000, v15
	v_lshlrev_b32_e32 v18, 16, v19
	v_and_b32_e32 v19, 0xffff0000, v19
	v_lshlrev_b32_e32 v228, 16, v21
	v_lshlrev_b32_e32 v211, 16, v17
	s_waitcnt vmcnt(3)
	v_pk_mul_f32 v[34:35], v[34:35], v[216:217]
	s_nop 0
	v_pk_fma_f32 v[30:31], v[30:31], v[196:197], v[34:35]
	s_waitcnt vmcnt(1)
	v_pk_fma_f32 v[30:31], v[212:213], v[218:219], v[30:31]
	s_nop 0
	v_mul_f32_e32 v6, 0xbfb8aa3b, v30
	v_exp_f32_e32 v6, v6
	s_nop 0
	v_add_f32_e32 v6, 1.0, v6
	v_rcp_f32_e32 v34, v6
	v_mul_f32_e32 v6, 0xbfb8aa3b, v31
	v_exp_f32_e32 v6, v6
	s_nop 0
	v_add_f32_e32 v6, 1.0, v6
	v_rcp_f32_e32 v35, v6
	v_lshlrev_b32_e32 v6, 16, v7
	v_and_b32_e32 v7, 0xffff0000, v7
	v_pk_mul_f32 v[6:7], v[36:37], v[6:7]
	v_pk_mul_f32 v[30:31], v[30:31], v[34:35]
	v_pk_fma_f32 v[6:7], v[32:33], v[14:15], v[6:7]
	v_and_b32_e32 v33, 0xffff0000, v20
	v_pk_fma_f32 v[6:7], v[214:215], v[18:19], v[6:7]
	v_and_b32_e32 v19, 0xffff0000, v8
	v_mul_f32_e32 v14, 0xbfb8aa3b, v6
	v_mul_f32_e32 v15, 0xbfb8aa3b, v7
	v_exp_f32_e32 v14, v14
	v_exp_f32_e32 v15, v15
	v_lshlrev_b32_e32 v18, 16, v8
	v_pk_mul_f32 v[10:11], v[10:11], v[18:19]
	v_add_f32_e32 v14, 1.0, v14
	v_add_f32_e32 v15, 1.0, v15
	v_rcp_f32_e32 v14, v14
	v_rcp_f32_e32 v15, v15
	v_lshlrev_b32_e32 v32, 16, v20
	v_and_b32_e32 v19, 0xffff0000, v21
	v_and_b32_e32 v18, 0xffff0000, v17
	v_pk_mul_f32 v[6:7], v[6:7], v[14:15]
	v_and_b32_e32 v15, 0xffff0000, v16
	v_lshlrev_b32_e32 v14, 16, v16
	v_pk_fma_f32 v[10:11], v[22:23], v[14:15], v[10:11]
	s_waitcnt vmcnt(0)
	v_pk_fma_f32 v[10:11], v[26:27], v[32:33], v[10:11]
	s_nop 0
	v_mul_f32_e32 v8, 0xbfb8aa3b, v10
	v_exp_f32_e32 v8, v8
	s_nop 0
	v_add_f32_e32 v8, 1.0, v8
	v_rcp_f32_e32 v14, v8
	v_mul_f32_e32 v8, 0xbfb8aa3b, v11
	v_exp_f32_e32 v8, v8
	s_nop 0
	v_add_f32_e32 v8, 1.0, v8
	v_rcp_f32_e32 v15, v8
	v_mul_f32_e32 v8, v24, v211
	v_pk_mul_f32 v[10:11], v[10:11], v[14:15]
	v_mul_f32_e32 v14, v28, v228
	v_mov_b32_e32 v28, v25
	v_pk_mul_f32 v[16:17], v[28:29], v[18:19]
	v_and_b32_e32 v19, 0xffff0000, v9
	v_lshlrev_b32_e32 v18, 16, v9
	v_mov_b32_e32 v9, v16
	v_pk_fma_f32 v[8:9], v[12:13], v[18:19], v[8:9]
	v_mov_b32_e32 v15, v17
	v_pk_add_f32 v[8:9], v[8:9], v[14:15]
	s_nop 0
	v_mul_f32_e32 v12, 0xbfb8aa3b, v8
	v_mul_f32_e32 v13, 0xbfb8aa3b, v9
	v_exp_f32_e32 v12, v12
	v_exp_f32_e32 v13, v13
	v_add_f32_e32 v12, 1.0, v12
	v_add_f32_e32 v13, 1.0, v13
	v_rcp_f32_e32 v12, v12
	v_rcp_f32_e32 v13, v13
	s_nop 0
	v_pk_mul_f32 v[8:9], v[8:9], v[12:13]
	s_mov_b64 s[26:27], exec
	v_readlane_b32 s4, v255, 42
	v_readlane_b32 s5, v255, 43
	s_and_b64 s[4:5], s[26:27], s[4:5]
	s_mov_b64 exec, s[4:5]
	s_cbranch_execz .LBB0_402
	v_pk_mul_f32 v[12:13], v[30:31], v[30:31]
	v_pk_mul_f32 v[14:15], v[6:7], v[6:7]
	v_add_f32_e32 v12, v12, v13
	v_add_f32_e32 v12, v14, v12
	v_pk_mul_f32 v[16:17], v[10:11], v[10:11]
	v_add_f32_e32 v12, v15, v12
	v_add_f32_e32 v12, v16, v12
	v_pk_mul_f32 v[18:19], v[8:9], v[8:9]
	v_add_f32_e32 v12, v17, v12
	v_add_f32_e32 v12, v18, v12
	v_add_f32_e32 v12, v19, v12
	s_nop 1
	v_add_f32_dpp v12, v12, v12 quad_perm:[1,0,3,2] row_mask:0xf bank_mask:0xf
	v_readlane_b32 s4, v255, 44
	v_readlane_b32 s5, v255, 45
	s_waitcnt lgkmcnt(0)
	s_nop 1
	v_add_f32_dpp v12, v12, v12 quad_perm:[2,3,0,1] row_mask:0xf bank_mask:0xf
	s_nop 1
	v_add_f32_dpp v12, v12, v12 row_half_mirror row_mask:0xf bank_mask:0xf
	s_nop 1
	v_add_f32_dpp v12, v12, v12 row_mirror row_mask:0xf bank_mask:0xf
	v_add_f32_e32 v12, 0x358637bd, v12
	v_rsq_f32_e32 v12, v12
	s_nop 0
	v_mul_f32_e32 v13, 0x3db504f3, v12
	v_cndmask_b32_e64 v12, v12, v13, s[4:5]
	v_pk_mul_f32 v[8:9], v[8:9], v[12:13] op_sel_hi:[1,0]
	v_pk_mul_f32 v[10:11], v[10:11], v[12:13] op_sel_hi:[1,0]
	v_pk_mul_f32 v[6:7], v[6:7], v[12:13] op_sel_hi:[1,0]
	v_pk_mul_f32 v[30:31], v[30:31], v[12:13] op_sel_hi:[1,0]

; __device__ __forceinline__ void gdn_prep_unit(LAS unsigned char* lds, unsigned char* ws, const float* conv_w, const float* a_log, const float* dt_bias,
;                                               int l, int Tp, int ci, int h, int nci, int nh, unsigned& pre_ba, int tid, int wave, int lane) {
;     ...
;         if (nci >= 0) { const bf16* pn = PROJ + (size_t)(nci * 64 + c) * LDP + C_BA; pre_ba = (unsigned)pn[d * 8 + nh] | ((unsigned)pn[16 + d * 8 + nh] << 16); }
;     ...
;         }
;     }
;     __syncthreads();
.LBB0_410:
	s_or_b64 exec, exec, s[26:27]
	v_readlane_b32 s4, v255, 50
	v_readlane_b32 s5, v255, 51
	s_andn2_b64 vcc, exec, s[4:5]
	s_mov_b32 s31, s52
	s_add_i32 s4, s7, s69
	s_cmpk_lt_u32 s4, 0x800
	s_cselect_b32 s4, 0x800, 0
	s_add_i32 s4, s4, s60
	s_and_b32 s5, s7, 7
	s_lshl_b32 s5, s5, 7
	v_or_b32_e32 v240, s4, v111
	v_or_b32_e32 v242, s5, v112
	v_mov_b64_e32 v[244:245], s[50:51]
	v_mov_b32_e32 v243, 0
	v_mad_i64_i32 v[240:241], s[84:85], v240, s70, v[244:245]
	s_mov_b64 s[16:17], 0x800
	v_lshl_add_u64 v[240:241], v[242:243], 1, v[240:241]
	s_sub_u32 s18, 0, s70
	s_subb_u32 s19, 0, 0
	v_lshl_add_u64 v[240:241], v[240:241], 0, s[16:17]
	s_lshl_b32 s16, s70, 5
	s_mov_b32 s17, 0
	global_load_dword v244, v[240:241], off offset:-2048
	global_load_dword v245, v[240:241], off
	global_load_dword v246, v[240:241], off offset:2048
	v_lshl_add_u64 v[242:243], v[240:241], 0, s[18:19]
	v_lshl_add_u64 v[240:241], v[240:241], 0, s[16:17]
	s_mov_b32 s16, s70
	global_load_dword v247, v[242:243], off offset:-2048
	global_load_dword v244, v[242:243], off
	global_load_dword v245, v[242:243], off offset:2048
	v_lshl_add_u64 v[242:243], v[240:241], 0, s[16:17]
	global_load_dword v246, v[240:241], off offset:-2048
	global_load_dword v247, v[240:241], off
	global_load_dword v244, v[240:241], off offset:2048
	global_load_dword v245, v[242:243], off offset:-2048
	global_load_dword v246, v[242:243], off
	global_load_dword v247, v[242:243], off offset:2048
	s_waitcnt lgkmcnt(0)
	s_barrier
	s_cbranch_vccnz .LBB0_481
	s_mov_b32 s16, s14
	s_branch .LBB0_414

; __device__ __forceinline__ unsigned cvt_pk_bf16(float lo, float hi) { const f32x2_c v = {lo, hi}; const bf16x2_c b = __builtin_convertvector(v, bf16x2_c); return __builtin_bit_cast(unsigned, b); }
;     __device__ __forceinline__ void operator()(const f32x4 (&acc)[2][2][4][2], const Unit& u, int wr, int wc, int fr, int fq) const {
;     ...
;                 for (int n = 0; n < 2; ++n) gn[bj][n] = *(const f32x4*)(gain_next + col0 + bj * HALF + n * 16); }
; #pragma unroll
;         for (int ai = 0; ai < 2; ++ai)
; #pragma unroll
;             for (int m2 = 0; m2 < 4; m2 += 2) {
;                 f32x4 bb[2][2][2];
; #pragma unroll
;                 for (int mm = 0; mm < 2; ++mm)
; #pragma unroll
;                     for (int bj = 0; bj < 2; ++bj)
; #pragma unroll
;                         for (int n = 0; n < 2; ++n) bb[mm][bj][n] = *(const f32x4*)(base + (size_t)(row0 + ai * HALF + (m2 + mm) * 16) * ldc + col0 + bj * HALF + n * 16);
; #pragma unroll
;                 for (int mm = 0; mm < 2; ++mm) { const int m = m2 + mm; const int row = row0 + ai * HALF + m * 16; const size_t off = (size_t)row * ldc + col0; float ss = 0.f;
; #pragma unroll
;                     for (int bj = 0; bj < 2; ++bj)
; #pragma unroll
;                         for (int n = 0; n < 2; ++n) { const f32x4 x = bb[mm][bj][n] + acc[ai][bj][m][n]; *(f32x4*)(out + off + bj * HALF + n * 16) = x;
;                             if (gain_next) { const f32x4 g = gn[bj][n]; ss += (x[0] * x[0] + x[1] * x[1]) + (x[2] * x[2] + x[3] * x[3]);
;                                 u32x2 w; w.x = cvt_pk_bf16(x[0] * g[0], x[1] * g[1]); w.y = cvt_pk_bf16(x[2] * g[2], x[3] * g[3]); *(u32x2*)(hn + off + bj * HALF + n * 16) = w; } }
;                     if (gain_next) {
;                         ss += __builtin_bit_cast(float, __builtin_amdgcn_ds_swizzle(__builtin_bit_cast(int, ss), 0x1F | (16 << 10)));
;                         ss += __shfl_xor(ss, 32);
;                         if (fq == 0) __hip_atomic_fetch_add(rowss + row, ss, __ATOMIC_RELAXED, __HIP_MEMORY_SCOPE_AGENT); } }
.LBB0_1509:
	v_readlane_b32 s14, v254, 23
	v_readlane_b32 s15, v254, 24
	v_and_b32_e32 v236, 16, v0
	v_lshrrev_b32_e32 v237, 1, v236
	v_add_u32_e32 v236, v236, v237
	v_mov_b32_e32 v237, 0
	s_nop 0
	v_lshl_add_u64 v[236:237], v[236:237], 0, s[14:15]
	v_lshl_or_b32 v206, s97, 8, v214
	v_cndmask_b32_e64 v66, 0, 1, s[26:27]
	v_cmp_ne_u32_e64 s[8:9], 1, v66
	s_andn2_b64 vcc, exec, s[26:27]
	v_ashrrev_i32_e32 v207, 31, v206
	v_readlane_b32 s93, v254, 14
	s_mov_b32 s31, s52
	s_cbranch_vccnz .LBB0_1511
	v_readlane_b32 s14, v254, 30
	v_readlane_b32 s15, v254, 31
	s_nop 1
	v_lshl_add_u64 v[66:67], v[206:207], 2, s[14:15]
	global_load_dwordx4 v[78:81], v[66:67], off
	global_load_dwordx4 v[74:77], v[66:67], off offset:64
	global_load_dwordx4 v[70:73], v[66:67], off offset:512
	s_nop 0
	global_load_dwordx4 v[66:69], v[66:67], off offset:576
.LBB0_1511:
	v_lshl_add_u32 v204, s29, 8, v5
	v_ashrrev_i32_e32 v205, 31, v204
	v_lshl_add_u64 v[208:209], v[206:207], 2, s[12:13]
	v_lshlrev_b64 v[158:159], 13, v[204:205]
	v_or_b32_e32 v210, 16, v204
	v_lshl_add_u64 v[158:159], v[208:209], 0, v[158:159]
	v_ashrrev_i32_e32 v211, 31, v210
	global_load_dwordx4 v[190:193], v[158:159], off
	global_load_dwordx4 v[182:185], v[158:159], off offset:64
	global_load_dwordx4 v[178:181], v[158:159], off offset:512
	global_load_dwordx4 v[174:177], v[158:159], off offset:576
	v_lshlrev_b64 v[158:159], 13, v[210:211]
	v_lshl_add_u64 v[158:159], v[208:209], 0, v[158:159]
	global_load_dwordx4 v[170:173], v[158:159], off
	global_load_dwordx4 v[166:169], v[158:159], off offset:64
	global_load_dwordx4 v[162:165], v[158:159], off offset:512
	s_nop 0
	global_load_dwordx4 v[158:161], v[158:159], off offset:576
	v_lshlrev_b64 v[186:187], 11, v[204:205]
	v_lshl_add_u64 v[188:189], v[186:187], 0, v[206:207]
	v_lshl_add_u64 v[212:213], v[188:189], 2, s[10:11]
	s_and_b64 vcc, exec, s[8:9]
	s_mov_b32 s69, s3
	s_waitcnt vmcnt(0)
	v_pk_add_f32 v[194:195], v[156:157], v[192:193]
	v_pk_add_f32 v[192:193], v[154:155], v[190:191]
	v_pk_add_f32 v[190:191], v[150:151], v[182:183]
	v_pk_add_f32 v[186:187], v[146:147], v[178:179]
	v_pk_add_f32 v[154:155], v[130:131], v[174:175]
	global_store_dwordx4 v[212:213], v[192:195], off
	s_cbranch_vccnz .LBB0_1554
	v_mul_f32_e32 v130, v193, v193
	v_mul_f32_e32 v131, v195, v195
	v_fmac_f32_e32 v130, v192, v192
	v_fmac_f32_e32 v131, v194, v194
	v_readlane_b32 s14, v254, 23
	v_add_f32_e32 v150, v130, v131
	v_pk_mul_f32 v[130:131], v[80:81], v[194:195]
	v_pk_mul_f32 v[146:147], v[78:79], v[192:193]
	v_readlane_b32 s15, v254, 24
	v_cvt_pk_bf16_f32 v216, v146, v147
	v_cvt_pk_bf16_f32 v217, v130, v131
	v_lshl_add_u64 v[130:131], v[188:189], 1, v[236:237]
	v_pk_add_f32 v[192:193], v[152:153], v[184:185]
	s_nop 0
	v_mul_f32_e32 v146, v191, v191
	v_mul_f32_e32 v147, v193, v193
	v_fmac_f32_e32 v146, v190, v190
	v_fmac_f32_e32 v147, v192, v192
	v_add_f32_e32 v146, v146, v147
	v_add_f32_e32 v156, v150, v146
	v_pk_mul_f32 v[146:147], v[76:77], v[192:193]
	v_pk_mul_f32 v[150:151], v[74:75], v[190:191]
	v_pk_add_f32 v[188:189], v[148:149], v[180:181]
	v_cvt_pk_bf16_f32 v218, v150, v151
	v_cvt_pk_bf16_f32 v219, v146, v147
	v_mul_f32_e32 v146, v187, v187
	v_mul_f32_e32 v147, v189, v189
	v_fmac_f32_e32 v146, v186, v186
	v_fmac_f32_e32 v147, v188, v188
	v_add_f32_e32 v146, v146, v147
	global_store_dwordx4 v[212:213], v[190:193], off offset:64
	s_nop 1
	v_permlane16_swap_b32_e32 v216, v218
	v_permlane16_swap_b32_e32 v217, v219
	global_store_dwordx4 v[130:131], v[216:219], off
	v_add_f32_e32 v174, v156, v146
	v_pk_mul_f32 v[146:147], v[72:73], v[188:189]
	v_pk_mul_f32 v[150:151], v[70:71], v[186:187]
	v_pk_add_f32 v[156:157], v[132:133], v[176:177]
	v_cvt_pk_bf16_f32 v228, v150, v151
	v_cvt_pk_bf16_f32 v229, v146, v147
	global_store_dwordx4 v[212:213], v[186:189], off offset:512
	s_nop 0
	v_pk_mul_f32 v[146:147], v[68:69], v[156:157]
	v_pk_mul_f32 v[150:151], v[66:67], v[154:155]
	global_store_dwordx4 v[212:213], v[154:157], off offset:576
	v_cvt_pk_bf16_f32 v230, v150, v151
	v_cvt_pk_bf16_f32 v231, v146, v147
	s_nop 1
	v_permlane16_swap_b32_e32 v228, v230
	v_permlane16_swap_b32_e32 v229, v231
	global_store_dwordx4 v[130:131], v[228:231], off offset:256
	v_mul_f32_e32 v130, v155, v155
	v_mul_f32_e32 v131, v157, v157
	v_fmac_f32_e32 v130, v154, v154
	v_fmac_f32_e32 v131, v156, v156
	v_add_f32_e32 v130, v130, v131
	v_add_f32_e32 v130, v174, v130
	ds_swizzle_b32 v131, v130 offset:swizzle(SWAP,16)
	v_and_b32_e32 v146, 64, v224
	v_add_u32_e32 v146, 64, v146
	s_waitcnt lgkmcnt(0)
	v_add_f32_e32 v130, v130, v131
	v_xor_b32_e32 v131, 32, v224
	v_cmp_lt_i32_e32 vcc, v131, v146
	s_nop 1
	v_cndmask_b32_e32 v131, v224, v131, vcc
	v_lshlrev_b32_e32 v131, 2, v131
	ds_bpermute_b32 v131, v131, v130
	s_and_saveexec_b64 s[76:77], s[4:5]
	s_cbranch_execz .LBB0_1514
	v_lshl_add_u64 v[146:147], v[204:205], 2, s[18:19]
	s_waitcnt lgkmcnt(0)
	v_add_f32_e32 v130, v130, v131
	global_atomic_add_f32 v[146:147], v130, off

; __device__ __forceinline__ unsigned cvt_pk_bf16(float lo, float hi) { const f32x2_c v = {lo, hi}; const bf16x2_c b = __builtin_convertvector(v, bf16x2_c); return __builtin_bit_cast(unsigned, b); }
;     __device__ __forceinline__ void operator()(const f32x4 (&acc)[2][2][4][2], const Unit& u, int wr, int wc, int fr, int fq) const {
;     ...
;                 for (int mm = 0; mm < 2; ++mm) { const int m = m2 + mm; const int row = row0 + ai * HALF + m * 16; const size_t off = (size_t)row * ldc + col0; float ss = 0.f;
; #pragma unroll
;                     for (int bj = 0; bj < 2; ++bj)
; #pragma unroll
;                         for (int n = 0; n < 2; ++n) { const f32x4 x = bb[mm][bj][n] + acc[ai][bj][m][n]; *(f32x4*)(out + off + bj * HALF + n * 16) = x;
;                             if (gain_next) { const f32x4 g = gn[bj][n]; ss += (x[0] * x[0] + x[1] * x[1]) + (x[2] * x[2] + x[3] * x[3]);
;                                 u32x2 w; w.x = cvt_pk_bf16(x[0] * g[0], x[1] * g[1]); w.y = cvt_pk_bf16(x[2] * g[2], x[3] * g[3]); *(u32x2*)(hn + off + bj * HALF + n * 16) = w; } }
;                     if (gain_next) {
;                         ss += __builtin_bit_cast(float, __builtin_amdgcn_ds_swizzle(__builtin_bit_cast(int, ss), 0x1F | (16 << 10)));
;                         ss += __shfl_xor(ss, 32);
;                         if (fq == 0) __hip_atomic_fetch_add(rowss + row, ss, __ATOMIC_RELAXED, __HIP_MEMORY_SCOPE_AGENT); } }
.LBB0_1516:
	s_waitcnt lgkmcnt(0)
	v_lshlrev_b64 v[130:131], 11, v[210:211]
	v_lshl_add_u64 v[132:133], v[130:131], 0, v[206:207]
	v_pk_add_f32 v[150:151], v[144:145], v[172:173]
	v_pk_add_f32 v[148:149], v[142:143], v[170:171]
	v_lshl_add_u64 v[152:153], v[132:133], 2, s[10:11]
	s_and_b64 vcc, exec, s[8:9]
	v_pk_add_f32 v[146:147], v[126:127], v[166:167]
	v_pk_add_f32 v[142:143], v[122:123], v[162:163]
	v_pk_add_f32 v[130:131], v[118:119], v[158:159]
	global_store_dwordx4 v[152:153], v[148:151], off
	s_cbranch_vccnz .LBB0_1555
	v_mul_f32_e32 v118, v149, v149
	v_mul_f32_e32 v119, v151, v151
	v_fmac_f32_e32 v118, v148, v148
	v_fmac_f32_e32 v119, v150, v150
	v_readlane_b32 s14, v254, 23
	v_add_f32_e32 v126, v118, v119
	v_pk_mul_f32 v[118:119], v[80:81], v[150:151]
	v_pk_mul_f32 v[122:123], v[78:79], v[148:149]
	v_readlane_b32 s15, v254, 24
	v_cvt_pk_bf16_f32 v216, v122, v123
	v_cvt_pk_bf16_f32 v217, v118, v119
	v_lshl_add_u64 v[118:119], v[132:133], 1, v[236:237]
	v_pk_add_f32 v[148:149], v[128:129], v[168:169]
	s_nop 0
	v_mul_f32_e32 v122, v147, v147
	v_mul_f32_e32 v123, v149, v149
	v_fmac_f32_e32 v122, v146, v146
	v_fmac_f32_e32 v123, v148, v148
	v_add_f32_e32 v122, v122, v123
	v_add_f32_e32 v132, v126, v122
	v_pk_mul_f32 v[122:123], v[76:77], v[148:149]
	v_pk_mul_f32 v[126:127], v[74:75], v[146:147]
	v_pk_add_f32 v[144:145], v[124:125], v[164:165]
	v_cvt_pk_bf16_f32 v218, v126, v127
	v_cvt_pk_bf16_f32 v219, v122, v123
	v_mul_f32_e32 v122, v143, v143
	v_mul_f32_e32 v123, v145, v145
	v_fmac_f32_e32 v122, v142, v142
	v_fmac_f32_e32 v123, v144, v144
	v_add_f32_e32 v122, v122, v123
	global_store_dwordx4 v[152:153], v[146:149], off offset:64
	s_nop 1
	v_permlane16_swap_b32_e32 v216, v218
	v_permlane16_swap_b32_e32 v217, v219
	global_store_dwordx4 v[118:119], v[216:219], off
	v_pk_mul_f32 v[126:127], v[70:71], v[142:143]
	v_add_f32_e32 v148, v132, v122
	v_pk_mul_f32 v[122:123], v[72:73], v[144:145]
	v_cvt_pk_bf16_f32 v228, v126, v127
	v_cvt_pk_bf16_f32 v229, v122, v123
	v_pk_add_f32 v[132:133], v[120:121], v[160:161]
	global_store_dwordx4 v[152:153], v[142:145], off offset:512
	s_nop 0
	v_pk_mul_f32 v[122:123], v[68:69], v[132:133]
	v_pk_mul_f32 v[126:127], v[66:67], v[130:131]
	global_store_dwordx4 v[152:153], v[130:133], off offset:576
	v_cvt_pk_bf16_f32 v230, v126, v127
	v_cvt_pk_bf16_f32 v231, v122, v123
	s_nop 1
	v_permlane16_swap_b32_e32 v228, v230
	v_permlane16_swap_b32_e32 v229, v231
	global_store_dwordx4 v[118:119], v[228:231], off offset:256
	v_mul_f32_e32 v118, v131, v131
	v_mul_f32_e32 v119, v133, v133
	v_fmac_f32_e32 v118, v130, v130
	v_fmac_f32_e32 v119, v132, v132
	v_add_f32_e32 v118, v118, v119
	v_add_f32_e32 v118, v148, v118
	ds_swizzle_b32 v119, v118 offset:swizzle(SWAP,16)
	v_and_b32_e32 v122, 64, v224
	v_add_u32_e32 v122, 64, v122
	s_waitcnt lgkmcnt(0)
	v_add_f32_e32 v118, v118, v119
	v_xor_b32_e32 v119, 32, v224
	v_cmp_lt_i32_e32 vcc, v119, v122
	s_nop 1
	v_cndmask_b32_e32 v119, v224, v119, vcc
	v_lshlrev_b32_e32 v119, 2, v119
	ds_bpermute_b32 v119, v119, v118
	s_and_saveexec_b64 s[76:77], s[4:5]
	s_cbranch_execz .LBB0_1519
	v_lshl_add_u64 v[122:123], v[204:205], 2, s[18:19]
	s_waitcnt lgkmcnt(0)
	v_add_f32_e32 v118, v118, v119
	global_atomic_add_f32 v[122:123], v118, off offset:64

; __device__ __forceinline__ unsigned cvt_pk_bf16(float lo, float hi) { const f32x2_c v = {lo, hi}; const bf16x2_c b = __builtin_convertvector(v, bf16x2_c); return __builtin_bit_cast(unsigned, b); }
;     __device__ __forceinline__ void operator()(const f32x4 (&acc)[2][2][4][2], const Unit& u, int wr, int wc, int fr, int fq) const {
;     ...
;                 for (int mm = 0; mm < 2; ++mm) { const int m = m2 + mm; const int row = row0 + ai * HALF + m * 16; const size_t off = (size_t)row * ldc + col0; float ss = 0.f;
; #pragma unroll
;                     for (int bj = 0; bj < 2; ++bj)
; #pragma unroll
;                         for (int n = 0; n < 2; ++n) { const f32x4 x = bb[mm][bj][n] + acc[ai][bj][m][n]; *(f32x4*)(out + off + bj * HALF + n * 16) = x;
;                             if (gain_next) { const f32x4 g = gn[bj][n]; ss += (x[0] * x[0] + x[1] * x[1]) + (x[2] * x[2] + x[3] * x[3]);
;                                 u32x2 w; w.x = cvt_pk_bf16(x[0] * g[0], x[1] * g[1]); w.y = cvt_pk_bf16(x[2] * g[2], x[3] * g[3]); *(u32x2*)(hn + off + bj * HALF + n * 16) = w; } }
;                     if (gain_next) {
;                         ss += __builtin_bit_cast(float, __builtin_amdgcn_ds_swizzle(__builtin_bit_cast(int, ss), 0x1F | (16 << 10)));
;                         ss += __shfl_xor(ss, 32);
;                         if (fq == 0) __hip_atomic_fetch_add(rowss + row, ss, __ATOMIC_RELAXED, __HIP_MEMORY_SCOPE_AGENT); } }
.LBB0_1521:
	v_or_b32_e32 v118, 32, v204
	s_waitcnt lgkmcnt(0)
	v_ashrrev_i32_e32 v119, 31, v118
	v_lshlrev_b64 v[154:155], 11, v[118:119]
	v_lshlrev_b64 v[118:119], 13, v[118:119]
	v_or_b32_e32 v164, 48, v204
	v_lshl_add_u64 v[118:119], v[208:209], 0, v[118:119]
	v_ashrrev_i32_e32 v165, 31, v164
	global_load_dwordx4 v[158:161], v[118:119], off
	global_load_dwordx4 v[150:153], v[118:119], off offset:64
	global_load_dwordx4 v[146:149], v[118:119], off offset:512
	global_load_dwordx4 v[142:145], v[118:119], off offset:576
	v_lshlrev_b64 v[118:119], 13, v[164:165]
	v_lshl_add_u64 v[118:119], v[208:209], 0, v[118:119]
	global_load_dwordx4 v[130:133], v[118:119], off
	global_load_dwordx4 v[126:129], v[118:119], off offset:64
	global_load_dwordx4 v[122:125], v[118:119], off offset:512
	s_nop 0
	global_load_dwordx4 v[118:121], v[118:119], off offset:576
	v_lshl_add_u64 v[156:157], v[154:155], 0, v[206:207]
	v_lshl_add_u64 v[166:167], v[156:157], 2, s[10:11]
	s_and_b64 vcc, exec, s[8:9]
	s_waitcnt vmcnt(7)
	v_pk_add_f32 v[162:163], v[116:117], v[160:161]
	v_pk_add_f32 v[160:161], v[114:115], v[158:159]
	s_waitcnt vmcnt(6)
	v_pk_add_f32 v[158:159], v[110:111], v[150:151]
	s_waitcnt vmcnt(5)
	v_pk_add_f32 v[154:155], v[106:107], v[146:147]
	s_waitcnt vmcnt(4)
	v_pk_add_f32 v[114:115], v[98:99], v[142:143]
	global_store_dwordx4 v[166:167], v[160:163], off
	s_cbranch_vccnz .LBB0_1556
	v_mul_f32_e32 v98, v161, v161
	v_mul_f32_e32 v99, v163, v163
	v_fmac_f32_e32 v98, v160, v160
	v_fmac_f32_e32 v99, v162, v162
	v_readlane_b32 s14, v254, 23
	v_add_f32_e32 v110, v98, v99
	v_pk_mul_f32 v[98:99], v[80:81], v[162:163]
	v_pk_mul_f32 v[106:107], v[78:79], v[160:161]
	v_readlane_b32 s15, v254, 24
	v_cvt_pk_bf16_f32 v216, v106, v107
	v_cvt_pk_bf16_f32 v217, v98, v99
	v_lshl_add_u64 v[98:99], v[156:157], 1, v[236:237]
	v_pk_add_f32 v[160:161], v[112:113], v[152:153]
	s_nop 0
	v_mul_f32_e32 v106, v159, v159
	v_mul_f32_e32 v107, v161, v161
	v_fmac_f32_e32 v106, v158, v158
	v_fmac_f32_e32 v107, v160, v160
	v_add_f32_e32 v106, v106, v107
	v_add_f32_e32 v116, v110, v106
	v_pk_mul_f32 v[106:107], v[76:77], v[160:161]
	v_pk_mul_f32 v[110:111], v[74:75], v[158:159]
	v_pk_add_f32 v[156:157], v[108:109], v[148:149]
	v_cvt_pk_bf16_f32 v218, v110, v111
	v_cvt_pk_bf16_f32 v219, v106, v107
	v_mul_f32_e32 v106, v155, v155
	v_mul_f32_e32 v107, v157, v157
	v_fmac_f32_e32 v106, v154, v154
	v_fmac_f32_e32 v107, v156, v156
	v_add_f32_e32 v106, v106, v107
	global_store_dwordx4 v[166:167], v[158:161], off offset:64
	s_nop 1
	v_permlane16_swap_b32_e32 v216, v218
	v_permlane16_swap_b32_e32 v217, v219
	global_store_dwordx4 v[98:99], v[216:219], off
	v_add_f32_e32 v142, v116, v106
	v_pk_mul_f32 v[106:107], v[72:73], v[156:157]
	v_pk_mul_f32 v[110:111], v[70:71], v[154:155]
	v_pk_add_f32 v[116:117], v[100:101], v[144:145]
	v_cvt_pk_bf16_f32 v228, v110, v111
	v_cvt_pk_bf16_f32 v229, v106, v107
	global_store_dwordx4 v[166:167], v[154:157], off offset:512
	s_nop 0
	v_pk_mul_f32 v[106:107], v[68:69], v[116:117]
	v_pk_mul_f32 v[110:111], v[66:67], v[114:115]
	global_store_dwordx4 v[166:167], v[114:117], off offset:576
	v_cvt_pk_bf16_f32 v230, v110, v111
	v_cvt_pk_bf16_f32 v231, v106, v107
	s_nop 1
	v_permlane16_swap_b32_e32 v228, v230
	v_permlane16_swap_b32_e32 v229, v231
	global_store_dwordx4 v[98:99], v[228:231], off offset:256
	v_mul_f32_e32 v98, v115, v115
	v_mul_f32_e32 v99, v117, v117
	v_fmac_f32_e32 v98, v114, v114
	v_fmac_f32_e32 v99, v116, v116
	v_add_f32_e32 v98, v98, v99
	v_add_f32_e32 v98, v142, v98
	ds_swizzle_b32 v99, v98 offset:swizzle(SWAP,16)
	v_and_b32_e32 v106, 64, v224
	v_add_u32_e32 v106, 64, v106
	s_waitcnt lgkmcnt(0)
	v_add_f32_e32 v98, v98, v99
	v_xor_b32_e32 v99, 32, v224
	v_cmp_lt_i32_e32 vcc, v99, v106
	s_nop 1
	v_cndmask_b32_e32 v99, v224, v99, vcc
	v_lshlrev_b32_e32 v99, 2, v99
	ds_bpermute_b32 v99, v99, v98
	s_and_saveexec_b64 s[76:77], s[4:5]
	s_cbranch_execz .LBB0_1524
	v_lshl_add_u64 v[106:107], v[204:205], 2, s[18:19]
	s_waitcnt lgkmcnt(0)
	v_add_f32_e32 v98, v98, v99
	global_atomic_add_f32 v[106:107], v98, off offset:128

; __device__ __forceinline__ unsigned cvt_pk_bf16(float lo, float hi) { const f32x2_c v = {lo, hi}; const bf16x2_c b = __builtin_convertvector(v, bf16x2_c); return __builtin_bit_cast(unsigned, b); }
;     __device__ __forceinline__ void operator()(const f32x4 (&acc)[2][2][4][2], const Unit& u, int wr, int wc, int fr, int fq) const {
;     ...
;                 for (int mm = 0; mm < 2; ++mm) { const int m = m2 + mm; const int row = row0 + ai * HALF + m * 16; const size_t off = (size_t)row * ldc + col0; float ss = 0.f;
; #pragma unroll
;                     for (int bj = 0; bj < 2; ++bj)
; #pragma unroll
;                         for (int n = 0; n < 2; ++n) { const f32x4 x = bb[mm][bj][n] + acc[ai][bj][m][n]; *(f32x4*)(out + off + bj * HALF + n * 16) = x;
;                             if (gain_next) { const f32x4 g = gn[bj][n]; ss += (x[0] * x[0] + x[1] * x[1]) + (x[2] * x[2] + x[3] * x[3]);
;                                 u32x2 w; w.x = cvt_pk_bf16(x[0] * g[0], x[1] * g[1]); w.y = cvt_pk_bf16(x[2] * g[2], x[3] * g[3]); *(u32x2*)(hn + off + bj * HALF + n * 16) = w; } }
;                     if (gain_next) {
;                         ss += __builtin_bit_cast(float, __builtin_amdgcn_ds_swizzle(__builtin_bit_cast(int, ss), 0x1F | (16 << 10)));
;                         ss += __shfl_xor(ss, 32);
;                         if (fq == 0) __hip_atomic_fetch_add(rowss + row, ss, __ATOMIC_RELAXED, __HIP_MEMORY_SCOPE_AGENT); } }
.LBB0_1526:
	s_waitcnt lgkmcnt(0)
	v_lshlrev_b64 v[98:99], 11, v[164:165]
	v_lshl_add_u64 v[100:101], v[98:99], 0, v[206:207]
	s_waitcnt vmcnt(4)
	v_pk_add_f32 v[110:111], v[104:105], v[132:133]
	v_pk_add_f32 v[108:109], v[102:103], v[130:131]
	v_lshl_add_u64 v[112:113], v[100:101], 2, s[10:11]
	s_and_b64 vcc, exec, s[8:9]
	s_waitcnt vmcnt(3)
	v_pk_add_f32 v[106:107], v[94:95], v[126:127]
	s_waitcnt vmcnt(2)
	v_pk_add_f32 v[102:103], v[90:91], v[122:123]
	s_waitcnt vmcnt(1)
	v_pk_add_f32 v[98:99], v[86:87], v[118:119]
	global_store_dwordx4 v[112:113], v[108:111], off
	s_cbranch_vccnz .LBB0_1557
	v_mul_f32_e32 v86, v109, v109
	v_mul_f32_e32 v87, v111, v111
	v_fmac_f32_e32 v86, v108, v108
	v_fmac_f32_e32 v87, v110, v110
	v_readlane_b32 s14, v254, 23
	v_add_f32_e32 v94, v86, v87
	v_pk_mul_f32 v[86:87], v[80:81], v[110:111]
	v_pk_mul_f32 v[90:91], v[78:79], v[108:109]
	v_readlane_b32 s15, v254, 24
	v_cvt_pk_bf16_f32 v216, v90, v91
	v_cvt_pk_bf16_f32 v217, v86, v87
	v_lshl_add_u64 v[86:87], v[100:101], 1, v[236:237]
	v_pk_add_f32 v[108:109], v[96:97], v[128:129]
	s_nop 0
	v_mul_f32_e32 v90, v107, v107
	v_mul_f32_e32 v91, v109, v109
	v_fmac_f32_e32 v90, v106, v106
	v_fmac_f32_e32 v91, v108, v108
	v_add_f32_e32 v90, v90, v91
	v_add_f32_e32 v100, v94, v90
	v_pk_mul_f32 v[90:91], v[76:77], v[108:109]
	v_pk_mul_f32 v[94:95], v[74:75], v[106:107]
	v_pk_add_f32 v[104:105], v[92:93], v[124:125]
	v_cvt_pk_bf16_f32 v218, v94, v95
	v_cvt_pk_bf16_f32 v219, v90, v91
	v_mul_f32_e32 v90, v103, v103
	v_mul_f32_e32 v91, v105, v105
	v_fmac_f32_e32 v90, v102, v102
	v_fmac_f32_e32 v91, v104, v104
	v_add_f32_e32 v90, v90, v91
	global_store_dwordx4 v[112:113], v[106:109], off offset:64
	s_nop 1
	v_permlane16_swap_b32_e32 v216, v218
	v_permlane16_swap_b32_e32 v217, v219
	global_store_dwordx4 v[86:87], v[216:219], off
	v_pk_mul_f32 v[94:95], v[70:71], v[102:103]
	v_add_f32_e32 v108, v100, v90
	v_pk_mul_f32 v[90:91], v[72:73], v[104:105]
	v_cvt_pk_bf16_f32 v228, v94, v95
	v_cvt_pk_bf16_f32 v229, v90, v91
	v_pk_add_f32 v[100:101], v[88:89], v[120:121]
	global_store_dwordx4 v[112:113], v[102:105], off offset:512
	s_nop 0
	v_pk_mul_f32 v[90:91], v[68:69], v[100:101]
	v_pk_mul_f32 v[94:95], v[66:67], v[98:99]
	global_store_dwordx4 v[112:113], v[98:101], off offset:576
	v_cvt_pk_bf16_f32 v230, v94, v95
	v_cvt_pk_bf16_f32 v231, v90, v91
	s_nop 1
	v_permlane16_swap_b32_e32 v228, v230
	v_permlane16_swap_b32_e32 v229, v231
	global_store_dwordx4 v[86:87], v[228:231], off offset:256
	v_mul_f32_e32 v86, v99, v99
	v_mul_f32_e32 v87, v101, v101
	v_fmac_f32_e32 v86, v98, v98
	v_fmac_f32_e32 v87, v100, v100
	v_add_f32_e32 v86, v86, v87
	v_add_f32_e32 v86, v108, v86
	ds_swizzle_b32 v87, v86 offset:swizzle(SWAP,16)
	v_and_b32_e32 v90, 64, v224
	v_add_u32_e32 v90, 64, v90
	s_waitcnt lgkmcnt(0)
	v_add_f32_e32 v86, v86, v87
	v_xor_b32_e32 v87, 32, v224
	v_cmp_lt_i32_e32 vcc, v87, v90
	s_nop 1
	v_cndmask_b32_e32 v87, v224, v87, vcc
	v_lshlrev_b32_e32 v87, 2, v87
	ds_bpermute_b32 v87, v87, v86
	s_and_saveexec_b64 s[76:77], s[4:5]
	s_cbranch_execz .LBB0_1529
	v_lshl_add_u64 v[90:91], v[204:205], 2, s[18:19]
	s_waitcnt lgkmcnt(0)
	v_add_f32_e32 v86, v86, v87
	global_atomic_add_f32 v[90:91], v86, off offset:192

; __device__ __forceinline__ unsigned cvt_pk_bf16(float lo, float hi) { const f32x2_c v = {lo, hi}; const bf16x2_c b = __builtin_convertvector(v, bf16x2_c); return __builtin_bit_cast(unsigned, b); }
;     __device__ __forceinline__ void operator()(const f32x4 (&acc)[2][2][4][2], const Unit& u, int wr, int wc, int fr, int fq) const {
;     ...
;                 for (int mm = 0; mm < 2; ++mm) { const int m = m2 + mm; const int row = row0 + ai * HALF + m * 16; const size_t off = (size_t)row * ldc + col0; float ss = 0.f;
; #pragma unroll
;                     for (int bj = 0; bj < 2; ++bj)
; #pragma unroll
;                         for (int n = 0; n < 2; ++n) { const f32x4 x = bb[mm][bj][n] + acc[ai][bj][m][n]; *(f32x4*)(out + off + bj * HALF + n * 16) = x;
;                             if (gain_next) { const f32x4 g = gn[bj][n]; ss += (x[0] * x[0] + x[1] * x[1]) + (x[2] * x[2] + x[3] * x[3]);
;                                 u32x2 w; w.x = cvt_pk_bf16(x[0] * g[0], x[1] * g[1]); w.y = cvt_pk_bf16(x[2] * g[2], x[3] * g[3]); *(u32x2*)(hn + off + bj * HALF + n * 16) = w; } }
;                     if (gain_next) {
;                         ss += __builtin_bit_cast(float, __builtin_amdgcn_ds_swizzle(__builtin_bit_cast(int, ss), 0x1F | (16 << 10)));
;                         ss += __shfl_xor(ss, 32);
;                         if (fq == 0) __hip_atomic_fetch_add(rowss + row, ss, __ATOMIC_RELAXED, __HIP_MEMORY_SCOPE_AGENT); } }
.LBB0_1531:
	v_add_u32_e32 v86, 0x80, v204
	s_waitcnt lgkmcnt(0)
	v_ashrrev_i32_e32 v87, 31, v86
	v_lshlrev_b64 v[114:115], 11, v[86:87]
	v_lshlrev_b64 v[86:87], 13, v[86:87]
	v_add_u32_e32 v124, 0x90, v204
	v_lshl_add_u64 v[86:87], v[208:209], 0, v[86:87]
	v_ashrrev_i32_e32 v125, 31, v124
	global_load_dwordx4 v[118:121], v[86:87], off
	global_load_dwordx4 v[110:113], v[86:87], off offset:64
	global_load_dwordx4 v[106:109], v[86:87], off offset:512
	global_load_dwordx4 v[102:105], v[86:87], off offset:576
	v_lshlrev_b64 v[86:87], 13, v[124:125]
	v_lshl_add_u64 v[86:87], v[208:209], 0, v[86:87]
	global_load_dwordx4 v[98:101], v[86:87], off
	global_load_dwordx4 v[94:97], v[86:87], off offset:64
	global_load_dwordx4 v[90:93], v[86:87], off offset:512
	s_nop 0
	global_load_dwordx4 v[86:89], v[86:87], off offset:576
	v_lshl_add_u64 v[116:117], v[114:115], 0, v[206:207]
	v_lshl_add_u64 v[126:127], v[116:117], 2, s[10:11]
	s_and_b64 vcc, exec, s[8:9]
	s_waitcnt vmcnt(7)
	v_pk_add_f32 v[122:123], v[84:85], v[120:121]
	v_pk_add_f32 v[120:121], v[82:83], v[118:119]
	s_waitcnt vmcnt(6)
	v_pk_add_f32 v[118:119], v[62:63], v[110:111]
	s_waitcnt vmcnt(5)
	v_pk_add_f32 v[114:115], v[58:59], v[106:107]
	s_waitcnt vmcnt(4)
	v_pk_add_f32 v[82:83], v[50:51], v[102:103]
	global_store_dwordx4 v[126:127], v[120:123], off
	s_cbranch_vccnz .LBB0_1558
	v_mul_f32_e32 v50, v121, v121
	v_mul_f32_e32 v51, v123, v123
	v_fmac_f32_e32 v50, v120, v120
	v_fmac_f32_e32 v51, v122, v122
	v_readlane_b32 s14, v254, 23
	v_add_f32_e32 v62, v50, v51
	v_pk_mul_f32 v[50:51], v[80:81], v[122:123]
	v_pk_mul_f32 v[58:59], v[78:79], v[120:121]
	v_readlane_b32 s15, v254, 24
	v_cvt_pk_bf16_f32 v216, v58, v59
	v_cvt_pk_bf16_f32 v217, v50, v51
	v_lshl_add_u64 v[50:51], v[116:117], 1, v[236:237]
	v_pk_add_f32 v[120:121], v[64:65], v[112:113]
	s_nop 0
	v_mul_f32_e32 v58, v119, v119
	v_mul_f32_e32 v59, v121, v121
	v_fmac_f32_e32 v58, v118, v118
	v_fmac_f32_e32 v59, v120, v120
	v_add_f32_e32 v58, v58, v59
	v_add_f32_e32 v84, v62, v58
	v_pk_mul_f32 v[58:59], v[76:77], v[120:121]
	v_pk_mul_f32 v[62:63], v[74:75], v[118:119]
	v_pk_add_f32 v[116:117], v[60:61], v[108:109]
	v_cvt_pk_bf16_f32 v218, v62, v63
	v_cvt_pk_bf16_f32 v219, v58, v59
	v_mul_f32_e32 v58, v115, v115
	v_mul_f32_e32 v59, v117, v117
	v_fmac_f32_e32 v58, v114, v114
	v_fmac_f32_e32 v59, v116, v116
	v_add_f32_e32 v58, v58, v59
	global_store_dwordx4 v[126:127], v[118:121], off offset:64
	s_nop 1
	v_permlane16_swap_b32_e32 v216, v218
	v_permlane16_swap_b32_e32 v217, v219
	global_store_dwordx4 v[50:51], v[216:219], off
	v_add_f32_e32 v102, v84, v58
	v_pk_mul_f32 v[58:59], v[72:73], v[116:117]
	v_pk_mul_f32 v[62:63], v[70:71], v[114:115]
	v_pk_add_f32 v[84:85], v[52:53], v[104:105]
	v_cvt_pk_bf16_f32 v228, v62, v63
	v_cvt_pk_bf16_f32 v229, v58, v59
	global_store_dwordx4 v[126:127], v[114:117], off offset:512
	s_nop 0
	v_pk_mul_f32 v[58:59], v[68:69], v[84:85]
	v_pk_mul_f32 v[62:63], v[66:67], v[82:83]
	global_store_dwordx4 v[126:127], v[82:85], off offset:576
	v_cvt_pk_bf16_f32 v230, v62, v63
	v_cvt_pk_bf16_f32 v231, v58, v59
	s_nop 1
	v_permlane16_swap_b32_e32 v228, v230
	v_permlane16_swap_b32_e32 v229, v231
	global_store_dwordx4 v[50:51], v[228:231], off offset:256
	v_mul_f32_e32 v50, v83, v83
	v_mul_f32_e32 v51, v85, v85
	v_fmac_f32_e32 v50, v82, v82
	v_fmac_f32_e32 v51, v84, v84
	v_add_f32_e32 v50, v50, v51
	v_add_f32_e32 v50, v102, v50
	ds_swizzle_b32 v51, v50 offset:swizzle(SWAP,16)
	v_and_b32_e32 v58, 64, v224
	v_add_u32_e32 v58, 64, v58
	s_waitcnt lgkmcnt(0)
	v_add_f32_e32 v50, v50, v51
	v_xor_b32_e32 v51, 32, v224
	v_cmp_lt_i32_e32 vcc, v51, v58
	s_nop 1
	v_cndmask_b32_e32 v51, v224, v51, vcc
	v_lshlrev_b32_e32 v51, 2, v51
	ds_bpermute_b32 v51, v51, v50
	s_and_saveexec_b64 s[76:77], s[4:5]
	s_cbranch_execz .LBB0_1534
	v_lshl_add_u64 v[58:59], v[204:205], 2, s[18:19]
	s_waitcnt lgkmcnt(0)
	v_add_f32_e32 v50, v50, v51
	global_atomic_add_f32 v[58:59], v50, off offset:512

; __device__ __forceinline__ unsigned cvt_pk_bf16(float lo, float hi) { const f32x2_c v = {lo, hi}; const bf16x2_c b = __builtin_convertvector(v, bf16x2_c); return __builtin_bit_cast(unsigned, b); }
;     __device__ __forceinline__ void operator()(const f32x4 (&acc)[2][2][4][2], const Unit& u, int wr, int wc, int fr, int fq) const {
;     ...
;                 for (int mm = 0; mm < 2; ++mm) { const int m = m2 + mm; const int row = row0 + ai * HALF + m * 16; const size_t off = (size_t)row * ldc + col0; float ss = 0.f;
; #pragma unroll
;                     for (int bj = 0; bj < 2; ++bj)
; #pragma unroll
;                         for (int n = 0; n < 2; ++n) { const f32x4 x = bb[mm][bj][n] + acc[ai][bj][m][n]; *(f32x4*)(out + off + bj * HALF + n * 16) = x;
;                             if (gain_next) { const f32x4 g = gn[bj][n]; ss += (x[0] * x[0] + x[1] * x[1]) + (x[2] * x[2] + x[3] * x[3]);
;                                 u32x2 w; w.x = cvt_pk_bf16(x[0] * g[0], x[1] * g[1]); w.y = cvt_pk_bf16(x[2] * g[2], x[3] * g[3]); *(u32x2*)(hn + off + bj * HALF + n * 16) = w; } }
;                     if (gain_next) {
;                         ss += __builtin_bit_cast(float, __builtin_amdgcn_ds_swizzle(__builtin_bit_cast(int, ss), 0x1F | (16 << 10)));
;                         ss += __shfl_xor(ss, 32);
;                         if (fq == 0) __hip_atomic_fetch_add(rowss + row, ss, __ATOMIC_RELAXED, __HIP_MEMORY_SCOPE_AGENT); } }
.LBB0_1536:
	s_waitcnt lgkmcnt(0)
	v_lshlrev_b64 v[50:51], 11, v[124:125]
	v_lshl_add_u64 v[52:53], v[50:51], 0, v[206:207]
	s_waitcnt vmcnt(4)
	v_pk_add_f32 v[62:63], v[56:57], v[100:101]
	v_pk_add_f32 v[60:61], v[54:55], v[98:99]
	v_lshl_add_u64 v[64:65], v[52:53], 2, s[10:11]
	s_and_b64 vcc, exec, s[8:9]
	s_waitcnt vmcnt(3)
	v_pk_add_f32 v[58:59], v[46:47], v[94:95]
	s_waitcnt vmcnt(2)
	v_pk_add_f32 v[54:55], v[42:43], v[90:91]
	s_waitcnt vmcnt(1)
	v_pk_add_f32 v[50:51], v[38:39], v[86:87]
	global_store_dwordx4 v[64:65], v[60:63], off
	s_cbranch_vccnz .LBB0_1559
	v_mul_f32_e32 v38, v61, v61
	v_mul_f32_e32 v39, v63, v63
	v_fmac_f32_e32 v38, v60, v60
	v_fmac_f32_e32 v39, v62, v62
	v_readlane_b32 s14, v254, 23
	v_add_f32_e32 v46, v38, v39
	v_pk_mul_f32 v[38:39], v[80:81], v[62:63]
	v_pk_mul_f32 v[42:43], v[78:79], v[60:61]
	v_readlane_b32 s15, v254, 24
	v_cvt_pk_bf16_f32 v216, v42, v43
	v_cvt_pk_bf16_f32 v217, v38, v39
	v_lshl_add_u64 v[38:39], v[52:53], 1, v[236:237]
	v_pk_add_f32 v[60:61], v[48:49], v[96:97]
	s_nop 0
	v_mul_f32_e32 v42, v59, v59
	v_mul_f32_e32 v43, v61, v61
	v_fmac_f32_e32 v42, v58, v58
	v_fmac_f32_e32 v43, v60, v60
	v_add_f32_e32 v42, v42, v43
	v_add_f32_e32 v52, v46, v42
	v_pk_mul_f32 v[42:43], v[76:77], v[60:61]
	v_pk_mul_f32 v[46:47], v[74:75], v[58:59]
	v_pk_add_f32 v[56:57], v[44:45], v[92:93]
	v_cvt_pk_bf16_f32 v218, v46, v47
	v_cvt_pk_bf16_f32 v219, v42, v43
	v_mul_f32_e32 v42, v55, v55
	v_mul_f32_e32 v43, v57, v57
	v_fmac_f32_e32 v42, v54, v54
	v_fmac_f32_e32 v43, v56, v56
	v_add_f32_e32 v42, v42, v43
	global_store_dwordx4 v[64:65], v[58:61], off offset:64
	s_nop 1
	v_permlane16_swap_b32_e32 v216, v218
	v_permlane16_swap_b32_e32 v217, v219
	global_store_dwordx4 v[38:39], v[216:219], off
	v_pk_mul_f32 v[46:47], v[70:71], v[54:55]
	v_add_f32_e32 v60, v52, v42
	v_pk_mul_f32 v[42:43], v[72:73], v[56:57]
	v_cvt_pk_bf16_f32 v228, v46, v47
	v_cvt_pk_bf16_f32 v229, v42, v43
	v_pk_add_f32 v[52:53], v[40:41], v[88:89]
	global_store_dwordx4 v[64:65], v[54:57], off offset:512
	s_nop 0
	v_pk_mul_f32 v[42:43], v[68:69], v[52:53]
	v_pk_mul_f32 v[46:47], v[66:67], v[50:51]
	global_store_dwordx4 v[64:65], v[50:53], off offset:576
	v_cvt_pk_bf16_f32 v230, v46, v47
	v_cvt_pk_bf16_f32 v231, v42, v43
	s_nop 1
	v_permlane16_swap_b32_e32 v228, v230
	v_permlane16_swap_b32_e32 v229, v231
	global_store_dwordx4 v[38:39], v[228:231], off offset:256
	v_mul_f32_e32 v38, v51, v51
	v_mul_f32_e32 v39, v53, v53
	v_fmac_f32_e32 v38, v50, v50
	v_fmac_f32_e32 v39, v52, v52
	v_add_f32_e32 v38, v38, v39
	v_add_f32_e32 v38, v60, v38
	ds_swizzle_b32 v39, v38 offset:swizzle(SWAP,16)
	v_and_b32_e32 v42, 64, v224
	v_add_u32_e32 v42, 64, v42
	s_waitcnt lgkmcnt(0)
	v_add_f32_e32 v38, v38, v39
	v_xor_b32_e32 v39, 32, v224
	v_cmp_lt_i32_e32 vcc, v39, v42
	s_nop 1
	v_cndmask_b32_e32 v39, v224, v39, vcc
	v_lshlrev_b32_e32 v39, 2, v39
	ds_bpermute_b32 v39, v39, v38
	s_and_saveexec_b64 s[76:77], s[4:5]
	s_cbranch_execz .LBB0_1539
	v_lshl_add_u64 v[42:43], v[204:205], 2, s[18:19]
	s_waitcnt lgkmcnt(0)
	v_add_f32_e32 v38, v38, v39
	global_atomic_add_f32 v[42:43], v38, off offset:576

; __device__ __forceinline__ unsigned cvt_pk_bf16(float lo, float hi) { const f32x2_c v = {lo, hi}; const bf16x2_c b = __builtin_convertvector(v, bf16x2_c); return __builtin_bit_cast(unsigned, b); }
;     __device__ __forceinline__ void operator()(const f32x4 (&acc)[2][2][4][2], const Unit& u, int wr, int wc, int fr, int fq) const {
;     ...
;                 for (int mm = 0; mm < 2; ++mm) { const int m = m2 + mm; const int row = row0 + ai * HALF + m * 16; const size_t off = (size_t)row * ldc + col0; float ss = 0.f;
; #pragma unroll
;                     for (int bj = 0; bj < 2; ++bj)
; #pragma unroll
;                         for (int n = 0; n < 2; ++n) { const f32x4 x = bb[mm][bj][n] + acc[ai][bj][m][n]; *(f32x4*)(out + off + bj * HALF + n * 16) = x;
;                             if (gain_next) { const f32x4 g = gn[bj][n]; ss += (x[0] * x[0] + x[1] * x[1]) + (x[2] * x[2] + x[3] * x[3]);
;                                 u32x2 w; w.x = cvt_pk_bf16(x[0] * g[0], x[1] * g[1]); w.y = cvt_pk_bf16(x[2] * g[2], x[3] * g[3]); *(u32x2*)(hn + off + bj * HALF + n * 16) = w; } }
;                     if (gain_next) {
;                         ss += __builtin_bit_cast(float, __builtin_amdgcn_ds_swizzle(__builtin_bit_cast(int, ss), 0x1F | (16 << 10)));
;                         ss += __shfl_xor(ss, 32);
;                         if (fq == 0) __hip_atomic_fetch_add(rowss + row, ss, __ATOMIC_RELAXED, __HIP_MEMORY_SCOPE_AGENT); } }
.LBB0_1541:
	v_add_u32_e32 v38, 0xa0, v204
	s_waitcnt lgkmcnt(0)
	v_ashrrev_i32_e32 v39, 31, v38
	v_lshlrev_b64 v[82:83], 11, v[38:39]
	v_lshlrev_b64 v[38:39], 13, v[38:39]
	v_add_u32_e32 v92, 0xb0, v204
	v_lshl_add_u64 v[38:39], v[208:209], 0, v[38:39]
	v_ashrrev_i32_e32 v93, 31, v92
	global_load_dwordx4 v[86:89], v[38:39], off
	global_load_dwordx4 v[62:65], v[38:39], off offset:64
	global_load_dwordx4 v[58:61], v[38:39], off offset:512
	global_load_dwordx4 v[54:57], v[38:39], off offset:576
	v_lshlrev_b64 v[38:39], 13, v[92:93]
	v_lshl_add_u64 v[38:39], v[208:209], 0, v[38:39]
	global_load_dwordx4 v[50:53], v[38:39], off
	global_load_dwordx4 v[46:49], v[38:39], off offset:64
	global_load_dwordx4 v[42:45], v[38:39], off offset:512
	s_nop 0
	global_load_dwordx4 v[38:41], v[38:39], off offset:576
	v_lshl_add_u64 v[84:85], v[82:83], 0, v[206:207]
	v_lshl_add_u64 v[94:95], v[84:85], 2, s[10:11]
	s_and_b64 vcc, exec, s[8:9]
	s_waitcnt vmcnt(7)
	v_pk_add_f32 v[90:91], v[36:37], v[88:89]
	v_pk_add_f32 v[88:89], v[34:35], v[86:87]
	s_waitcnt vmcnt(6)
	v_pk_add_f32 v[86:87], v[30:31], v[62:63]
	s_waitcnt vmcnt(5)
	v_pk_add_f32 v[82:83], v[26:27], v[58:59]
	s_waitcnt vmcnt(4)
	v_pk_add_f32 v[34:35], v[18:19], v[54:55]
	global_store_dwordx4 v[94:95], v[88:91], off
	s_cbranch_vccnz .LBB0_1560
	v_mul_f32_e32 v18, v89, v89
	v_mul_f32_e32 v19, v91, v91
	v_fmac_f32_e32 v18, v88, v88
	v_fmac_f32_e32 v19, v90, v90
	v_readlane_b32 s14, v254, 23
	v_add_f32_e32 v30, v18, v19
	v_pk_mul_f32 v[18:19], v[80:81], v[90:91]
	v_pk_mul_f32 v[26:27], v[78:79], v[88:89]
	v_readlane_b32 s15, v254, 24
	v_cvt_pk_bf16_f32 v216, v26, v27
	v_cvt_pk_bf16_f32 v217, v18, v19
	v_lshl_add_u64 v[18:19], v[84:85], 1, v[236:237]
	v_pk_add_f32 v[88:89], v[32:33], v[64:65]
	s_nop 0
	v_mul_f32_e32 v26, v87, v87
	v_mul_f32_e32 v27, v89, v89
	v_fmac_f32_e32 v26, v86, v86
	v_fmac_f32_e32 v27, v88, v88
	v_add_f32_e32 v26, v26, v27
	v_add_f32_e32 v36, v30, v26
	v_pk_mul_f32 v[26:27], v[76:77], v[88:89]
	v_pk_mul_f32 v[30:31], v[74:75], v[86:87]
	v_pk_add_f32 v[84:85], v[28:29], v[60:61]
	v_cvt_pk_bf16_f32 v218, v30, v31
	v_cvt_pk_bf16_f32 v219, v26, v27
	v_mul_f32_e32 v26, v83, v83
	v_mul_f32_e32 v27, v85, v85
	v_fmac_f32_e32 v26, v82, v82
	v_fmac_f32_e32 v27, v84, v84
	v_add_f32_e32 v26, v26, v27
	global_store_dwordx4 v[94:95], v[86:89], off offset:64
	s_nop 1
	v_permlane16_swap_b32_e32 v216, v218
	v_permlane16_swap_b32_e32 v217, v219
	global_store_dwordx4 v[18:19], v[216:219], off
	v_add_f32_e32 v54, v36, v26
	v_pk_mul_f32 v[26:27], v[72:73], v[84:85]
	v_pk_mul_f32 v[30:31], v[70:71], v[82:83]
	v_pk_add_f32 v[36:37], v[20:21], v[56:57]
	v_cvt_pk_bf16_f32 v228, v30, v31
	v_cvt_pk_bf16_f32 v229, v26, v27
	global_store_dwordx4 v[94:95], v[82:85], off offset:512
	s_nop 0
	v_pk_mul_f32 v[26:27], v[68:69], v[36:37]
	v_pk_mul_f32 v[30:31], v[66:67], v[34:35]
	global_store_dwordx4 v[94:95], v[34:37], off offset:576
	v_cvt_pk_bf16_f32 v230, v30, v31
	v_cvt_pk_bf16_f32 v231, v26, v27
	s_nop 1
	v_permlane16_swap_b32_e32 v228, v230
	v_permlane16_swap_b32_e32 v229, v231
	global_store_dwordx4 v[18:19], v[228:231], off offset:256
	v_mul_f32_e32 v18, v35, v35
	v_mul_f32_e32 v19, v37, v37
	v_fmac_f32_e32 v18, v34, v34
	v_fmac_f32_e32 v19, v36, v36
	v_add_f32_e32 v18, v18, v19
	v_add_f32_e32 v18, v54, v18
	ds_swizzle_b32 v19, v18 offset:swizzle(SWAP,16)
	v_and_b32_e32 v26, 64, v224
	v_add_u32_e32 v26, 64, v26
	s_waitcnt lgkmcnt(0)
	v_add_f32_e32 v18, v18, v19
	v_xor_b32_e32 v19, 32, v224
	v_cmp_lt_i32_e32 vcc, v19, v26
	s_nop 1
	v_cndmask_b32_e32 v19, v224, v19, vcc
	v_lshlrev_b32_e32 v19, 2, v19
	ds_bpermute_b32 v19, v19, v18
	s_and_saveexec_b64 s[76:77], s[4:5]
	s_cbranch_execz .LBB0_1544
	v_lshl_add_u64 v[26:27], v[204:205], 2, s[18:19]
	s_waitcnt lgkmcnt(0)
	v_add_f32_e32 v18, v18, v19
	global_atomic_add_f32 v[26:27], v18, off offset:640

; __device__ __forceinline__ unsigned cvt_pk_bf16(float lo, float hi) { const f32x2_c v = {lo, hi}; const bf16x2_c b = __builtin_convertvector(v, bf16x2_c); return __builtin_bit_cast(unsigned, b); }
;     __device__ __forceinline__ void operator()(const f32x4 (&acc)[2][2][4][2], const Unit& u, int wr, int wc, int fr, int fq) const {
;     ...
;                 for (int mm = 0; mm < 2; ++mm) { const int m = m2 + mm; const int row = row0 + ai * HALF + m * 16; const size_t off = (size_t)row * ldc + col0; float ss = 0.f;
; #pragma unroll
;                     for (int bj = 0; bj < 2; ++bj)
; #pragma unroll
;                         for (int n = 0; n < 2; ++n) { const f32x4 x = bb[mm][bj][n] + acc[ai][bj][m][n]; *(f32x4*)(out + off + bj * HALF + n * 16) = x;
;                             if (gain_next) { const f32x4 g = gn[bj][n]; ss += (x[0] * x[0] + x[1] * x[1]) + (x[2] * x[2] + x[3] * x[3]);
;                                 u32x2 w; w.x = cvt_pk_bf16(x[0] * g[0], x[1] * g[1]); w.y = cvt_pk_bf16(x[2] * g[2], x[3] * g[3]); *(u32x2*)(hn + off + bj * HALF + n * 16) = w; } }
;                     if (gain_next) {
;                         ss += __builtin_bit_cast(float, __builtin_amdgcn_ds_swizzle(__builtin_bit_cast(int, ss), 0x1F | (16 << 10)));
;                         ss += __shfl_xor(ss, 32);
;                         if (fq == 0) __hip_atomic_fetch_add(rowss + row, ss, __ATOMIC_RELAXED, __HIP_MEMORY_SCOPE_AGENT); } }
.LBB0_1546:
	s_waitcnt lgkmcnt(0)
	v_lshlrev_b64 v[18:19], 11, v[92:93]
	v_lshl_add_u64 v[20:21], v[18:19], 0, v[206:207]
	s_waitcnt vmcnt(4)
	v_pk_add_f32 v[30:31], v[24:25], v[52:53]
	v_pk_add_f32 v[28:29], v[22:23], v[50:51]
	v_lshl_add_u64 v[32:33], v[20:21], 2, s[10:11]
	s_and_b64 vcc, exec, s[8:9]
	s_waitcnt vmcnt(3)
	v_pk_add_f32 v[26:27], v[14:15], v[46:47]
	s_waitcnt vmcnt(2)
	v_pk_add_f32 v[22:23], v[10:11], v[42:43]
	s_waitcnt vmcnt(1)
	v_pk_add_f32 v[18:19], v[6:7], v[38:39]
	global_store_dwordx4 v[32:33], v[28:31], off
	s_cbranch_vccnz .LBB0_1561
	v_mul_f32_e32 v6, v29, v29
	v_mul_f32_e32 v7, v31, v31
	v_fmac_f32_e32 v6, v28, v28
	v_fmac_f32_e32 v7, v30, v30
	v_add_f32_e32 v24, v6, v7
	v_pk_mul_f32 v[6:7], v[80:81], v[30:31]
	v_pk_mul_f32 v[10:11], v[78:79], v[28:29]
	v_pk_add_f32 v[28:29], v[16:17], v[48:49]
	v_cvt_pk_bf16_f32 v216, v10, v11
	v_cvt_pk_bf16_f32 v217, v6, v7
	v_readlane_b32 s8, v254, 23
	v_mul_f32_e32 v6, v27, v27
	v_mul_f32_e32 v7, v29, v29
	v_readlane_b32 s9, v254, 24
	v_fmac_f32_e32 v6, v26, v26
	v_fmac_f32_e32 v7, v28, v28
	v_lshl_add_u64 v[14:15], v[20:21], 1, v[236:237]
	v_add_f32_e32 v6, v6, v7
	s_nop 0
	v_add_f32_e32 v20, v24, v6
	v_pk_mul_f32 v[6:7], v[76:77], v[28:29]
	v_pk_mul_f32 v[10:11], v[74:75], v[26:27]
	v_pk_add_f32 v[24:25], v[12:13], v[44:45]
	v_cvt_pk_bf16_f32 v218, v10, v11
	v_cvt_pk_bf16_f32 v219, v6, v7
	v_mul_f32_e32 v6, v23, v23
	v_mul_f32_e32 v7, v25, v25
	v_fmac_f32_e32 v6, v22, v22
	v_fmac_f32_e32 v7, v24, v24
	v_add_f32_e32 v6, v6, v7
	global_store_dwordx4 v[32:33], v[26:29], off offset:64
	s_nop 1
	v_permlane16_swap_b32_e32 v216, v218
	v_permlane16_swap_b32_e32 v217, v219
	global_store_dwordx4 v[14:15], v[216:219], off
	v_pk_mul_f32 v[10:11], v[70:71], v[22:23]
	v_add_f32_e32 v28, v20, v6
	v_pk_add_f32 v[20:21], v[8:9], v[40:41]
	global_store_dwordx4 v[32:33], v[22:25], off offset:512
	v_pk_mul_f32 v[6:7], v[72:73], v[24:25]
	v_cvt_pk_bf16_f32 v228, v10, v11
	v_mul_f32_e32 v11, v19, v19
	v_mul_f32_e32 v24, v21, v21
	v_fmac_f32_e32 v11, v18, v18
	v_fmac_f32_e32 v24, v20, v20
	v_add_f32_e32 v11, v11, v24
	v_add_f32_e32 v24, v28, v11
	ds_swizzle_b32 v25, v24 offset:swizzle(SWAP,16)
	v_cvt_pk_bf16_f32 v229, v6, v7
	s_nop 0
	global_store_dwordx4 v[32:33], v[18:21], off offset:576
	v_pk_mul_f32 v[10:11], v[68:69], v[20:21]
	v_xor_b32_e32 v7, 32, v224
	v_and_b32_e32 v20, 64, v224
	v_add_u32_e32 v20, 64, v20
	v_cmp_lt_i32_e32 vcc, v7, v20
	s_waitcnt lgkmcnt(0)
	v_add_f32_e32 v6, v24, v25
	v_pk_mul_f32 v[20:21], v[66:67], v[18:19]
	v_cndmask_b32_e32 v7, v224, v7, vcc
	v_lshlrev_b32_e32 v7, 2, v7
	ds_bpermute_b32 v7, v7, v6
	v_cvt_pk_bf16_f32 v230, v20, v21
	v_cvt_pk_bf16_f32 v231, v10, v11
	s_nop 1
	v_permlane16_swap_b32_e32 v228, v230
	v_permlane16_swap_b32_e32 v229, v231
	global_store_dwordx4 v[14:15], v[228:231], off offset:256
	s_and_saveexec_b64 s[8:9], s[4:5]
	s_cbranch_execz .LBB0_1549
	v_lshl_add_u64 v[10:11], v[204:205], 2, s[18:19]
	s_waitcnt lgkmcnt(0)
	v_add_f32_e32 v6, v6, v7
	global_atomic_add_f32 v[10:11], v6, off offset:704
